# EpiMerge LDS variant with the LDS reads software-pipelined one step ahead
# baseline (speedup 1.0000x reference)
; #define EPI_FOR(u) \
;     _Pragma("unroll") for (int ai = 0; ai < 2; ++ai) _Pragma("unroll") for (int m = 0; m < 4; ++m) _Pragma("unroll") for (int bj = 0; bj < 2; ++bj)
; #define EPI_COL(u) (EPI_CB(u) + 8 * fq)
;     DI void operator()(const Acc& acc, const Unit& u, int wr, int wc, int fr, int fq) const {
;         EPI_FOR(u) {
;             const int row = EPI_ROW(u), col = EPI_COL(u); EPI_V(v);
;             const u32x4 gg = *(const u32x4*)(gate + (size_t)row * 3072 + gi * 1024 + col);
;             const float gf[8] = {bflo(gg.x), bfhi(gg.x), bflo(gg.y), bfhi(gg.y), bflo(gg.z), bfhi(gg.z), bflo(gg.w), bfhi(gg.w)};
;             bf16_t* mp = mrg + (size_t)row * 1024 + col;
;             if (accum) {
.LBB0_1061:
	s_lshl_b32 s2, s28, 8
	s_lshl_b32 s6, s29, 8
	v_readfirstlane_b32 s7, v232
	s_lshr_b32 s7, s7, 6
	s_lshl_b32 s7, s7, 4
	v_add_u32_e32 v210, s51, v145
	v_lshlrev_b32_e32 v210, 10, v210
	v_and_b32_e32 v211, 7, v145
	v_lshlrev_b32_e32 v212, 1, v144
	v_xor_b32_e32 v211, v212, v211
	v_lshl_add_u32 v210, v211, 4, v210
	s_lshl_b32 s8, s54, 2
	v_add_u32_e32 v210, s8, v210
	v_xor_b32_e32 v211, 16, v210
	v_lshrrev_b32_e32 v212, 5, v233
	v_and_b32_e32 v213, 31, v233
	v_lshl_add_u32 v214, v213, 3, s6
	v_lshlrev_b32_e32 v214, 1, v214
	v_lshlrev_b32_e32 v213, 1, v213

; #define EPI_FOR(u) \
;     _Pragma("unroll") for (int ai = 0; ai < 2; ++ai) _Pragma("unroll") for (int m = 0; m < 4; ++m) _Pragma("unroll") for (int bj = 0; bj < 2; ++bj)
; #define EPI_COL(u) (EPI_CB(u) + 8 * fq)
; DI u32x4 pack8(const float* v) { u32x4 w; w.x = pk2(v[0], v[1]); w.y = pk2(v[2], v[3]); w.z = pk2(v[4], v[5]); w.w = pk2(v[6], v[7]); return w; }
;     DI void operator()(const Acc& acc, const Unit& u, int wr, int wc, int fr, int fq) const {
;         EPI_FOR(u) {
;             const int row = EPI_ROW(u), col = EPI_COL(u); EPI_V(v);
;             const u32x4 gg = *(const u32x4*)(gate + (size_t)row * 3072 + gi * 1024 + col);
;             const float gf[8] = {bflo(gg.x), bfhi(gg.x), bflo(gg.y), bfhi(gg.y), bflo(gg.z), bfhi(gg.z), bflo(gg.w), bfhi(gg.w)};
;             bf16_t* mp = mrg + (size_t)row * 1024 + col;
;             if (accum) {
;                 const u32x4 oo = *(const u32x4*)mp;
;                 const float of[8] = {bflo(oo.x), bfhi(oo.x), bflo(oo.y), bfhi(oo.y), bflo(oo.z), bfhi(oo.z), bflo(oo.w), bfhi(oo.w)};
; #pragma unroll
;                 for (int j = 0; j < 8; ++j) v[j] = of[j] + gf[j] * v[j];
;             } else {
; #pragma unroll
;                 for (int j = 0; j < 8; ++j) v[j] = gf[j] * v[j];
;             }
;             *(u32x4*)mp = pack8(v);
;         }
	v_add_u32_e32 v215, s7, v212
	s_add_i32 s8, s2, 0
	v_add_u32_e32 v216, s8, v215
	v_mul_u32_u24_e32 v217, 0x1800, v216
	v_add_u32_e32 v217, v217, v214
	v_add_u32_e32 v217, 0x0, v217
	v_lshl_add_u32 v218, v216, 11, v214
	global_load_dwordx4 v[128:131], v217, s[22:23]
	v_add_u32_e32 v219, 0x3000, v217
	global_load_dwordx4 v[132:135], v219, s[22:23]
	v_add_u32_e32 v219, 0x6000, v217
	global_load_dwordx4 v[136:139], v219, s[22:23]
	v_add_u32_e32 v219, 0x9000, v217
	global_load_dwordx4 v[140:143], v219, s[22:23]
	v_add_u32_e32 v219, 0xc000, v217
	global_load_dwordx4 v[144:147], v219, s[22:23]
	v_add_u32_e32 v219, 0xf000, v217
	global_load_dwordx4 v[148:151], v219, s[22:23]
	v_add_u32_e32 v219, 0x12000, v217
	global_load_dwordx4 v[152:155], v219, s[22:23]
	v_add_u32_e32 v219, 0x15000, v217
	global_load_dwordx4 v[156:159], v219, s[22:23]
	s_waitcnt vmcnt(8)
	s_barrier
	ds_write_b128 v210, v[124:127]
	ds_write_b128 v211, v[120:123]
	ds_write_b128 v210, v[116:119] offset:512
	ds_write_b128 v211, v[112:115] offset:512
	ds_write_b128 v210, v[108:111] offset:16384
	ds_write_b128 v211, v[104:107] offset:16384
	ds_write_b128 v210, v[100:103] offset:16896
	ds_write_b128 v211, v[96:99] offset:16896
	ds_write_b128 v210, v[92:95] offset:32768
	ds_write_b128 v211, v[88:91] offset:32768
	ds_write_b128 v210, v[84:87] offset:33280
	ds_write_b128 v211, v[80:83] offset:33280
	ds_write_b128 v210, v[76:79] offset:49152
	ds_write_b128 v211, v[72:75] offset:49152
	ds_write_b128 v210, v[68:71] offset:49664
	ds_write_b128 v211, v[64:67] offset:49664
	s_waitcnt lgkmcnt(0)
	s_barrier
	v_add_u32_e32 v219, 0, v212
	v_and_b32_e32 v219, 7, v219
	v_xor_b32_e32 v219, v213, v219
	v_add_u32_e32 v188, 0, v215
	v_lshlrev_b32_e32 v188, 10, v188
	v_lshl_add_u32 v219, v219, 4, v188
	v_xor_b32_e32 v188, 16, v219
	ds_read_b128 v[244:247], v219
	ds_read_b128 v[220:223], v188
	v_add_u32_e32 v219, 2, v212
	v_and_b32_e32 v219, 7, v219
	v_xor_b32_e32 v219, v213, v219
	v_add_u32_e32 v188, 2, v215
	v_lshlrev_b32_e32 v188, 10, v188
	v_lshl_add_u32 v219, v219, 4, v188
	v_xor_b32_e32 v188, 16, v219
	ds_read_b128 v[234:237], v219
	ds_read_b128 v[228:231], v188
	s_waitcnt vmcnt(7)
	s_waitcnt lgkmcnt(2)
	v_lshlrev_b32_e32 v184, 16, v128
	v_and_b32_e32 v185, 0xffff0000, v128
	v_pk_mul_f32 v[244:245], v[244:245], v[184:185]
	v_lshlrev_b32_e32 v184, 16, v129
	v_and_b32_e32 v185, 0xffff0000, v129
	v_pk_mul_f32 v[246:247], v[246:247], v[184:185]
	v_lshlrev_b32_e32 v184, 16, v130
	v_and_b32_e32 v185, 0xffff0000, v130
	v_pk_mul_f32 v[220:221], v[220:221], v[184:185]
	v_lshlrev_b32_e32 v184, 16, v131
	v_and_b32_e32 v185, 0xffff0000, v131
	v_pk_mul_f32 v[222:223], v[222:223], v[184:185]
	v_cvt_pk_bf16_f32 v128, v244, v245
	v_cvt_pk_bf16_f32 v129, v246, v247
	v_cvt_pk_bf16_f32 v130, v220, v221
	v_cvt_pk_bf16_f32 v131, v222, v223
	global_store_dwordx4 v218, v[128:131], s[24:25]
	v_add_u32_e32 v219, 4, v212
	v_and_b32_e32 v219, 7, v219
	v_xor_b32_e32 v219, v213, v219
	v_add_u32_e32 v188, 4, v215
	v_lshlrev_b32_e32 v188, 10, v188
	v_lshl_add_u32 v219, v219, 4, v188
	v_xor_b32_e32 v188, 16, v219
	ds_read_b128 v[244:247], v219
	ds_read_b128 v[220:223], v188
	s_waitcnt vmcnt(7)
	s_waitcnt lgkmcnt(2)
	v_lshlrev_b32_e32 v184, 16, v132
	v_and_b32_e32 v185, 0xffff0000, v132
	v_pk_mul_f32 v[234:235], v[234:235], v[184:185]
	v_lshlrev_b32_e32 v184, 16, v133
	v_and_b32_e32 v185, 0xffff0000, v133
	v_pk_mul_f32 v[236:237], v[236:237], v[184:185]
	v_lshlrev_b32_e32 v184, 16, v134
	v_and_b32_e32 v185, 0xffff0000, v134
	v_pk_mul_f32 v[228:229], v[228:229], v[184:185]
	v_lshlrev_b32_e32 v184, 16, v135
	v_and_b32_e32 v185, 0xffff0000, v135
	v_pk_mul_f32 v[230:231], v[230:231], v[184:185]
	v_cvt_pk_bf16_f32 v132, v234, v235
	v_cvt_pk_bf16_f32 v133, v236, v237
	v_cvt_pk_bf16_f32 v134, v228, v229
	v_cvt_pk_bf16_f32 v135, v230, v231
	v_add_u32_e32 v219, 0x1000, v218
	global_store_dwordx4 v219, v[132:135], s[24:25]
	v_add_u32_e32 v219, 6, v212
	v_and_b32_e32 v219, 7, v219
	v_xor_b32_e32 v219, v213, v219
	v_add_u32_e32 v188, 6, v215
	v_lshlrev_b32_e32 v188, 10, v188
	v_lshl_add_u32 v219, v219, 4, v188
	v_xor_b32_e32 v188, 16, v219
	ds_read_b128 v[234:237], v219
	ds_read_b128 v[228:231], v188
	s_waitcnt vmcnt(7)
	s_waitcnt lgkmcnt(2)
	v_lshlrev_b32_e32 v184, 16, v136
	v_and_b32_e32 v185, 0xffff0000, v136
	v_pk_mul_f32 v[244:245], v[244:245], v[184:185]
	v_lshlrev_b32_e32 v184, 16, v137
	v_and_b32_e32 v185, 0xffff0000, v137
	v_pk_mul_f32 v[246:247], v[246:247], v[184:185]
	v_lshlrev_b32_e32 v184, 16, v138
	v_and_b32_e32 v185, 0xffff0000, v138
	v_pk_mul_f32 v[220:221], v[220:221], v[184:185]
	v_lshlrev_b32_e32 v184, 16, v139
	v_and_b32_e32 v185, 0xffff0000, v139
	v_pk_mul_f32 v[222:223], v[222:223], v[184:185]
	v_cvt_pk_bf16_f32 v136, v244, v245
	v_cvt_pk_bf16_f32 v137, v246, v247
	v_cvt_pk_bf16_f32 v138, v220, v221
	v_cvt_pk_bf16_f32 v139, v222, v223
	v_add_u32_e32 v219, 0x2000, v218
	global_store_dwordx4 v219, v[136:139], s[24:25]
	v_add_u32_e32 v219, 8, v212
	v_and_b32_e32 v219, 7, v219
	v_xor_b32_e32 v219, v213, v219
	v_add_u32_e32 v188, 8, v215
	v_lshlrev_b32_e32 v188, 10, v188
	v_lshl_add_u32 v219, v219, 4, v188
	v_xor_b32_e32 v188, 16, v219
	ds_read_b128 v[244:247], v219
	ds_read_b128 v[220:223], v188
	s_waitcnt vmcnt(7)
	s_waitcnt lgkmcnt(2)
; #define EPI_FOR(u) \
;     _Pragma("unroll") for (int ai = 0; ai < 2; ++ai) _Pragma("unroll") for (int m = 0; m < 4; ++m) _Pragma("unroll") for (int bj = 0; bj < 2; ++bj)
; #define EPI_COL(u) (EPI_CB(u) + 8 * fq)
; DI u32x4 pack8(const float* v) { u32x4 w; w.x = pk2(v[0], v[1]); w.y = pk2(v[2], v[3]); w.z = pk2(v[4], v[5]); w.w = pk2(v[6], v[7]); return w; }
;     DI void operator()(const Acc& acc, const Unit& u, int wr, int wc, int fr, int fq) const {
;         EPI_FOR(u) {
;             const int row = EPI_ROW(u), col = EPI_COL(u); EPI_V(v);
;             const u32x4 gg = *(const u32x4*)(gate + (size_t)row * 3072 + gi * 1024 + col);
;             const float gf[8] = {bflo(gg.x), bfhi(gg.x), bflo(gg.y), bfhi(gg.y), bflo(gg.z), bfhi(gg.z), bflo(gg.w), bfhi(gg.w)};
;             bf16_t* mp = mrg + (size_t)row * 1024 + col;
;             if (accum) {
;                 const u32x4 oo = *(const u32x4*)mp;
;                 const float of[8] = {bflo(oo.x), bfhi(oo.x), bflo(oo.y), bfhi(oo.y), bflo(oo.z), bfhi(oo.z), bflo(oo.w), bfhi(oo.w)};
; #pragma unroll
;                 for (int j = 0; j < 8; ++j) v[j] = of[j] + gf[j] * v[j];
;             } else {
; #pragma unroll
;                 for (int j = 0; j < 8; ++j) v[j] = gf[j] * v[j];
;             }
;             *(u32x4*)mp = pack8(v);
;         }
	v_lshlrev_b32_e32 v184, 16, v140
	v_and_b32_e32 v185, 0xffff0000, v140
	v_pk_mul_f32 v[234:235], v[234:235], v[184:185]
	v_lshlrev_b32_e32 v184, 16, v141
	v_and_b32_e32 v185, 0xffff0000, v141
	v_pk_mul_f32 v[236:237], v[236:237], v[184:185]
	v_lshlrev_b32_e32 v184, 16, v142
	v_and_b32_e32 v185, 0xffff0000, v142
	v_pk_mul_f32 v[228:229], v[228:229], v[184:185]
	v_lshlrev_b32_e32 v184, 16, v143
	v_and_b32_e32 v185, 0xffff0000, v143
	v_pk_mul_f32 v[230:231], v[230:231], v[184:185]
	v_cvt_pk_bf16_f32 v140, v234, v235
	v_cvt_pk_bf16_f32 v141, v236, v237
	v_cvt_pk_bf16_f32 v142, v228, v229
	v_cvt_pk_bf16_f32 v143, v230, v231
	v_add_u32_e32 v219, 0x3000, v218
	global_store_dwordx4 v219, v[140:143], s[24:25]
	v_add_u32_e32 v219, 10, v212
	v_and_b32_e32 v219, 7, v219
	v_xor_b32_e32 v219, v213, v219
	v_add_u32_e32 v188, 10, v215
	v_lshlrev_b32_e32 v188, 10, v188
	v_lshl_add_u32 v219, v219, 4, v188
	v_xor_b32_e32 v188, 16, v219
	ds_read_b128 v[234:237], v219
	ds_read_b128 v[228:231], v188
	s_waitcnt vmcnt(7)
	s_waitcnt lgkmcnt(2)
	v_lshlrev_b32_e32 v184, 16, v144
	v_and_b32_e32 v185, 0xffff0000, v144
	v_pk_mul_f32 v[244:245], v[244:245], v[184:185]
	v_lshlrev_b32_e32 v184, 16, v145
	v_and_b32_e32 v185, 0xffff0000, v145
	v_pk_mul_f32 v[246:247], v[246:247], v[184:185]
	v_lshlrev_b32_e32 v184, 16, v146
	v_and_b32_e32 v185, 0xffff0000, v146
	v_pk_mul_f32 v[220:221], v[220:221], v[184:185]
	v_lshlrev_b32_e32 v184, 16, v147
	v_and_b32_e32 v185, 0xffff0000, v147
	v_pk_mul_f32 v[222:223], v[222:223], v[184:185]
	v_cvt_pk_bf16_f32 v144, v244, v245
	v_cvt_pk_bf16_f32 v145, v246, v247
	v_cvt_pk_bf16_f32 v146, v220, v221
	v_cvt_pk_bf16_f32 v147, v222, v223
	v_add_u32_e32 v219, 0x4000, v218
	global_store_dwordx4 v219, v[144:147], s[24:25]
	v_add_u32_e32 v219, 12, v212
	v_and_b32_e32 v219, 7, v219
	v_xor_b32_e32 v219, v213, v219
	v_add_u32_e32 v188, 12, v215
	v_lshlrev_b32_e32 v188, 10, v188
	v_lshl_add_u32 v219, v219, 4, v188
	v_xor_b32_e32 v188, 16, v219
	ds_read_b128 v[244:247], v219
	ds_read_b128 v[220:223], v188
	s_waitcnt vmcnt(7)
	s_waitcnt lgkmcnt(2)
	v_lshlrev_b32_e32 v184, 16, v148
	v_and_b32_e32 v185, 0xffff0000, v148
	v_pk_mul_f32 v[234:235], v[234:235], v[184:185]
	v_lshlrev_b32_e32 v184, 16, v149
	v_and_b32_e32 v185, 0xffff0000, v149
	v_pk_mul_f32 v[236:237], v[236:237], v[184:185]
	v_lshlrev_b32_e32 v184, 16, v150
	v_and_b32_e32 v185, 0xffff0000, v150
	v_pk_mul_f32 v[228:229], v[228:229], v[184:185]
	v_lshlrev_b32_e32 v184, 16, v151
	v_and_b32_e32 v185, 0xffff0000, v151
	v_pk_mul_f32 v[230:231], v[230:231], v[184:185]
	v_cvt_pk_bf16_f32 v148, v234, v235
	v_cvt_pk_bf16_f32 v149, v236, v237
	v_cvt_pk_bf16_f32 v150, v228, v229
	v_cvt_pk_bf16_f32 v151, v230, v231
	v_add_u32_e32 v219, 0x5000, v218
	global_store_dwordx4 v219, v[148:151], s[24:25]
	v_add_u32_e32 v219, 14, v212
	v_and_b32_e32 v219, 7, v219
	v_xor_b32_e32 v219, v213, v219
	v_add_u32_e32 v188, 14, v215
	v_lshlrev_b32_e32 v188, 10, v188
	v_lshl_add_u32 v219, v219, 4, v188
	v_xor_b32_e32 v188, 16, v219
	ds_read_b128 v[234:237], v219
	ds_read_b128 v[228:231], v188
	s_waitcnt vmcnt(7)
	s_waitcnt lgkmcnt(2)
	v_lshlrev_b32_e32 v184, 16, v152
	v_and_b32_e32 v185, 0xffff0000, v152
	v_pk_mul_f32 v[244:245], v[244:245], v[184:185]
	v_lshlrev_b32_e32 v184, 16, v153
	v_and_b32_e32 v185, 0xffff0000, v153
	v_pk_mul_f32 v[246:247], v[246:247], v[184:185]
	v_lshlrev_b32_e32 v184, 16, v154
	v_and_b32_e32 v185, 0xffff0000, v154
	v_pk_mul_f32 v[220:221], v[220:221], v[184:185]
	v_lshlrev_b32_e32 v184, 16, v155
	v_and_b32_e32 v185, 0xffff0000, v155
	v_pk_mul_f32 v[222:223], v[222:223], v[184:185]
	v_cvt_pk_bf16_f32 v152, v244, v245
	v_cvt_pk_bf16_f32 v153, v246, v247
	v_cvt_pk_bf16_f32 v154, v220, v221
	v_cvt_pk_bf16_f32 v155, v222, v223
	v_add_u32_e32 v219, 0x6000, v218
	global_store_dwordx4 v219, v[152:155], s[24:25]
	s_waitcnt vmcnt(7)
	s_waitcnt lgkmcnt(0)
	v_lshlrev_b32_e32 v184, 16, v156
	v_and_b32_e32 v185, 0xffff0000, v156
	v_pk_mul_f32 v[234:235], v[234:235], v[184:185]
	v_lshlrev_b32_e32 v184, 16, v157
	v_and_b32_e32 v185, 0xffff0000, v157
	v_pk_mul_f32 v[236:237], v[236:237], v[184:185]
	v_lshlrev_b32_e32 v184, 16, v158
	v_and_b32_e32 v185, 0xffff0000, v158
	v_pk_mul_f32 v[228:229], v[228:229], v[184:185]
	v_lshlrev_b32_e32 v184, 16, v159
	v_and_b32_e32 v185, 0xffff0000, v159
	v_pk_mul_f32 v[230:231], v[230:231], v[184:185]
	v_cvt_pk_bf16_f32 v156, v234, v235
	v_cvt_pk_bf16_f32 v157, v236, v237
	v_cvt_pk_bf16_f32 v158, v228, v229
	v_cvt_pk_bf16_f32 v159, v230, v231
	v_add_u32_e32 v219, 0x7000, v218
	global_store_dwordx4 v219, v[156:159], s[24:25]
	v_add_u32_e32 v215, s7, v212
	s_add_i32 s8, s2, 128
	v_add_u32_e32 v216, s8, v215
	v_mul_u32_u24_e32 v217, 0x1800, v216
	v_add_u32_e32 v217, v217, v214
	v_add_u32_e32 v217, 0x0, v217
	v_lshl_add_u32 v218, v216, 11, v214
	global_load_dwordx4 v[128:131], v217, s[22:23]
	v_add_u32_e32 v219, 0x3000, v217
	global_load_dwordx4 v[132:135], v219, s[22:23]
	v_add_u32_e32 v219, 0x6000, v217
	global_load_dwordx4 v[136:139], v219, s[22:23]
	v_add_u32_e32 v219, 0x9000, v217
	global_load_dwordx4 v[140:143], v219, s[22:23]
	v_add_u32_e32 v219, 0xc000, v217
	global_load_dwordx4 v[144:147], v219, s[22:23]
	v_add_u32_e32 v219, 0xf000, v217
	global_load_dwordx4 v[148:151], v219, s[22:23]
	v_add_u32_e32 v219, 0x12000, v217
	global_load_dwordx4 v[152:155], v219, s[22:23]
	v_add_u32_e32 v219, 0x15000, v217
	global_load_dwordx4 v[156:159], v219, s[22:23]
	s_barrier
; #define EPI_FOR(u) \
;     _Pragma("unroll") for (int ai = 0; ai < 2; ++ai) _Pragma("unroll") for (int m = 0; m < 4; ++m) _Pragma("unroll") for (int bj = 0; bj < 2; ++bj)
; #define EPI_COL(u) (EPI_CB(u) + 8 * fq)
; DI u32x4 pack8(const float* v) { u32x4 w; w.x = pk2(v[0], v[1]); w.y = pk2(v[2], v[3]); w.z = pk2(v[4], v[5]); w.w = pk2(v[6], v[7]); return w; }
;     DI void operator()(const Acc& acc, const Unit& u, int wr, int wc, int fr, int fq) const {
;         EPI_FOR(u) {
;             const int row = EPI_ROW(u), col = EPI_COL(u); EPI_V(v);
;             const u32x4 gg = *(const u32x4*)(gate + (size_t)row * 3072 + gi * 1024 + col);
;             const float gf[8] = {bflo(gg.x), bfhi(gg.x), bflo(gg.y), bfhi(gg.y), bflo(gg.z), bfhi(gg.z), bflo(gg.w), bfhi(gg.w)};
;             bf16_t* mp = mrg + (size_t)row * 1024 + col;
;             if (accum) {
;                 const u32x4 oo = *(const u32x4*)mp;
;                 const float of[8] = {bflo(oo.x), bfhi(oo.x), bflo(oo.y), bfhi(oo.y), bflo(oo.z), bfhi(oo.z), bflo(oo.w), bfhi(oo.w)};
; #pragma unroll
;                 for (int j = 0; j < 8; ++j) v[j] = of[j] + gf[j] * v[j];
;             } else {
; #pragma unroll
;                 for (int j = 0; j < 8; ++j) v[j] = gf[j] * v[j];
;             }
;             *(u32x4*)mp = pack8(v);
;         }
	ds_write_b128 v210, v[60:63]
	ds_write_b128 v211, v[56:59]
	ds_write_b128 v210, v[52:55] offset:512
	ds_write_b128 v211, v[48:51] offset:512
	ds_write_b128 v210, v[44:47] offset:16384
	ds_write_b128 v211, v[40:43] offset:16384
	ds_write_b128 v210, v[36:39] offset:16896
	ds_write_b128 v211, v[32:35] offset:16896
	ds_write_b128 v210, v[28:31] offset:32768
	ds_write_b128 v211, v[24:27] offset:32768
	ds_write_b128 v210, v[20:23] offset:33280
	ds_write_b128 v211, v[16:19] offset:33280
	ds_write_b128 v210, v[12:15] offset:49152
	ds_write_b128 v211, v[8:11] offset:49152
	ds_write_b128 v210, v[4:7] offset:49664
	ds_write_b128 v211, v[0:3] offset:49664
	s_waitcnt lgkmcnt(0)
	s_barrier
	v_add_u32_e32 v219, 0, v212
	v_and_b32_e32 v219, 7, v219
	v_xor_b32_e32 v219, v213, v219
	v_add_u32_e32 v188, 0, v215
	v_lshlrev_b32_e32 v188, 10, v188
	v_lshl_add_u32 v219, v219, 4, v188
	v_xor_b32_e32 v188, 16, v219
	ds_read_b128 v[244:247], v219
	ds_read_b128 v[220:223], v188
	v_add_u32_e32 v219, 2, v212
	v_and_b32_e32 v219, 7, v219
	v_xor_b32_e32 v219, v213, v219
	v_add_u32_e32 v188, 2, v215
	v_lshlrev_b32_e32 v188, 10, v188
	v_lshl_add_u32 v219, v219, 4, v188
	v_xor_b32_e32 v188, 16, v219
	ds_read_b128 v[234:237], v219
	ds_read_b128 v[228:231], v188
	s_waitcnt vmcnt(7)
	s_waitcnt lgkmcnt(2)
	v_lshlrev_b32_e32 v184, 16, v128
	v_and_b32_e32 v185, 0xffff0000, v128
	v_pk_mul_f32 v[244:245], v[244:245], v[184:185]
	v_lshlrev_b32_e32 v184, 16, v129
	v_and_b32_e32 v185, 0xffff0000, v129
	v_pk_mul_f32 v[246:247], v[246:247], v[184:185]
	v_lshlrev_b32_e32 v184, 16, v130
	v_and_b32_e32 v185, 0xffff0000, v130
	v_pk_mul_f32 v[220:221], v[220:221], v[184:185]
	v_lshlrev_b32_e32 v184, 16, v131
	v_and_b32_e32 v185, 0xffff0000, v131
	v_pk_mul_f32 v[222:223], v[222:223], v[184:185]
	v_cvt_pk_bf16_f32 v128, v244, v245
	v_cvt_pk_bf16_f32 v129, v246, v247
	v_cvt_pk_bf16_f32 v130, v220, v221
	v_cvt_pk_bf16_f32 v131, v222, v223
	global_store_dwordx4 v218, v[128:131], s[24:25]
	v_add_u32_e32 v219, 4, v212
	v_and_b32_e32 v219, 7, v219
	v_xor_b32_e32 v219, v213, v219
	v_add_u32_e32 v188, 4, v215
	v_lshlrev_b32_e32 v188, 10, v188
	v_lshl_add_u32 v219, v219, 4, v188
	v_xor_b32_e32 v188, 16, v219
	ds_read_b128 v[244:247], v219
	ds_read_b128 v[220:223], v188
	s_waitcnt vmcnt(7)
	s_waitcnt lgkmcnt(2)
	v_lshlrev_b32_e32 v184, 16, v132
	v_and_b32_e32 v185, 0xffff0000, v132
	v_pk_mul_f32 v[234:235], v[234:235], v[184:185]
	v_lshlrev_b32_e32 v184, 16, v133
	v_and_b32_e32 v185, 0xffff0000, v133
	v_pk_mul_f32 v[236:237], v[236:237], v[184:185]
	v_lshlrev_b32_e32 v184, 16, v134
	v_and_b32_e32 v185, 0xffff0000, v134
	v_pk_mul_f32 v[228:229], v[228:229], v[184:185]
	v_lshlrev_b32_e32 v184, 16, v135
	v_and_b32_e32 v185, 0xffff0000, v135
	v_pk_mul_f32 v[230:231], v[230:231], v[184:185]
	v_cvt_pk_bf16_f32 v132, v234, v235
	v_cvt_pk_bf16_f32 v133, v236, v237
	v_cvt_pk_bf16_f32 v134, v228, v229
	v_cvt_pk_bf16_f32 v135, v230, v231
	v_add_u32_e32 v219, 0x1000, v218
	global_store_dwordx4 v219, v[132:135], s[24:25]
	v_add_u32_e32 v219, 6, v212
	v_and_b32_e32 v219, 7, v219
	v_xor_b32_e32 v219, v213, v219
	v_add_u32_e32 v188, 6, v215
	v_lshlrev_b32_e32 v188, 10, v188
	v_lshl_add_u32 v219, v219, 4, v188
	v_xor_b32_e32 v188, 16, v219
	ds_read_b128 v[234:237], v219
	ds_read_b128 v[228:231], v188
	s_waitcnt vmcnt(7)
	s_waitcnt lgkmcnt(2)
	v_lshlrev_b32_e32 v184, 16, v136
	v_and_b32_e32 v185, 0xffff0000, v136
	v_pk_mul_f32 v[244:245], v[244:245], v[184:185]
	v_lshlrev_b32_e32 v184, 16, v137
	v_and_b32_e32 v185, 0xffff0000, v137
	v_pk_mul_f32 v[246:247], v[246:247], v[184:185]
	v_lshlrev_b32_e32 v184, 16, v138
	v_and_b32_e32 v185, 0xffff0000, v138
	v_pk_mul_f32 v[220:221], v[220:221], v[184:185]
	v_lshlrev_b32_e32 v184, 16, v139
	v_and_b32_e32 v185, 0xffff0000, v139
	v_pk_mul_f32 v[222:223], v[222:223], v[184:185]
	v_cvt_pk_bf16_f32 v136, v244, v245
	v_cvt_pk_bf16_f32 v137, v246, v247
	v_cvt_pk_bf16_f32 v138, v220, v221
	v_cvt_pk_bf16_f32 v139, v222, v223
	v_add_u32_e32 v219, 0x2000, v218
	global_store_dwordx4 v219, v[136:139], s[24:25]
	v_add_u32_e32 v219, 8, v212
	v_and_b32_e32 v219, 7, v219
	v_xor_b32_e32 v219, v213, v219
	v_add_u32_e32 v188, 8, v215
	v_lshlrev_b32_e32 v188, 10, v188
	v_lshl_add_u32 v219, v219, 4, v188
	v_xor_b32_e32 v188, 16, v219
	ds_read_b128 v[244:247], v219
	ds_read_b128 v[220:223], v188
	s_waitcnt vmcnt(7)
	s_waitcnt lgkmcnt(2)
; #define EPI_FOR(u) \
;     _Pragma("unroll") for (int ai = 0; ai < 2; ++ai) _Pragma("unroll") for (int m = 0; m < 4; ++m) _Pragma("unroll") for (int bj = 0; bj < 2; ++bj)
; #define EPI_COL(u) (EPI_CB(u) + 8 * fq)
; DI u32x4 pack8(const float* v) { u32x4 w; w.x = pk2(v[0], v[1]); w.y = pk2(v[2], v[3]); w.z = pk2(v[4], v[5]); w.w = pk2(v[6], v[7]); return w; }
;     DI void operator()(const Acc& acc, const Unit& u, int wr, int wc, int fr, int fq) const {
;         EPI_FOR(u) {
;             const int row = EPI_ROW(u), col = EPI_COL(u); EPI_V(v);
;             const u32x4 gg = *(const u32x4*)(gate + (size_t)row * 3072 + gi * 1024 + col);
;             const float gf[8] = {bflo(gg.x), bfhi(gg.x), bflo(gg.y), bfhi(gg.y), bflo(gg.z), bfhi(gg.z), bflo(gg.w), bfhi(gg.w)};
;             bf16_t* mp = mrg + (size_t)row * 1024 + col;
;             if (accum) {
;                 const u32x4 oo = *(const u32x4*)mp;
;                 const float of[8] = {bflo(oo.x), bfhi(oo.x), bflo(oo.y), bfhi(oo.y), bflo(oo.z), bfhi(oo.z), bflo(oo.w), bfhi(oo.w)};
; #pragma unroll
;                 for (int j = 0; j < 8; ++j) v[j] = of[j] + gf[j] * v[j];
;             } else {
; #pragma unroll
;                 for (int j = 0; j < 8; ++j) v[j] = gf[j] * v[j];
;             }
;             *(u32x4*)mp = pack8(v);
;         }
	v_lshlrev_b32_e32 v184, 16, v140
	v_and_b32_e32 v185, 0xffff0000, v140
	v_pk_mul_f32 v[234:235], v[234:235], v[184:185]
	v_lshlrev_b32_e32 v184, 16, v141
	v_and_b32_e32 v185, 0xffff0000, v141
	v_pk_mul_f32 v[236:237], v[236:237], v[184:185]
	v_lshlrev_b32_e32 v184, 16, v142
	v_and_b32_e32 v185, 0xffff0000, v142
	v_pk_mul_f32 v[228:229], v[228:229], v[184:185]
	v_lshlrev_b32_e32 v184, 16, v143
	v_and_b32_e32 v185, 0xffff0000, v143
	v_pk_mul_f32 v[230:231], v[230:231], v[184:185]
	v_cvt_pk_bf16_f32 v140, v234, v235
	v_cvt_pk_bf16_f32 v141, v236, v237
	v_cvt_pk_bf16_f32 v142, v228, v229
	v_cvt_pk_bf16_f32 v143, v230, v231
	v_add_u32_e32 v219, 0x3000, v218
	global_store_dwordx4 v219, v[140:143], s[24:25]
	v_add_u32_e32 v219, 10, v212
	v_and_b32_e32 v219, 7, v219
	v_xor_b32_e32 v219, v213, v219
	v_add_u32_e32 v188, 10, v215
	v_lshlrev_b32_e32 v188, 10, v188
	v_lshl_add_u32 v219, v219, 4, v188
	v_xor_b32_e32 v188, 16, v219
	ds_read_b128 v[234:237], v219
	ds_read_b128 v[228:231], v188
	s_waitcnt vmcnt(7)
	s_waitcnt lgkmcnt(2)
	v_lshlrev_b32_e32 v184, 16, v144
	v_and_b32_e32 v185, 0xffff0000, v144
	v_pk_mul_f32 v[244:245], v[244:245], v[184:185]
	v_lshlrev_b32_e32 v184, 16, v145
	v_and_b32_e32 v185, 0xffff0000, v145
	v_pk_mul_f32 v[246:247], v[246:247], v[184:185]
	v_lshlrev_b32_e32 v184, 16, v146
	v_and_b32_e32 v185, 0xffff0000, v146
	v_pk_mul_f32 v[220:221], v[220:221], v[184:185]
	v_lshlrev_b32_e32 v184, 16, v147
	v_and_b32_e32 v185, 0xffff0000, v147
	v_pk_mul_f32 v[222:223], v[222:223], v[184:185]
	v_cvt_pk_bf16_f32 v144, v244, v245
	v_cvt_pk_bf16_f32 v145, v246, v247
	v_cvt_pk_bf16_f32 v146, v220, v221
	v_cvt_pk_bf16_f32 v147, v222, v223
	v_add_u32_e32 v219, 0x4000, v218
	global_store_dwordx4 v219, v[144:147], s[24:25]
	v_add_u32_e32 v219, 12, v212
	v_and_b32_e32 v219, 7, v219
	v_xor_b32_e32 v219, v213, v219
	v_add_u32_e32 v188, 12, v215
	v_lshlrev_b32_e32 v188, 10, v188
	v_lshl_add_u32 v219, v219, 4, v188
	v_xor_b32_e32 v188, 16, v219
	ds_read_b128 v[244:247], v219
	ds_read_b128 v[220:223], v188
	s_waitcnt vmcnt(7)
	s_waitcnt lgkmcnt(2)
	v_lshlrev_b32_e32 v184, 16, v148
	v_and_b32_e32 v185, 0xffff0000, v148
	v_pk_mul_f32 v[234:235], v[234:235], v[184:185]
	v_lshlrev_b32_e32 v184, 16, v149
	v_and_b32_e32 v185, 0xffff0000, v149
	v_pk_mul_f32 v[236:237], v[236:237], v[184:185]
	v_lshlrev_b32_e32 v184, 16, v150
	v_and_b32_e32 v185, 0xffff0000, v150
	v_pk_mul_f32 v[228:229], v[228:229], v[184:185]
	v_lshlrev_b32_e32 v184, 16, v151
	v_and_b32_e32 v185, 0xffff0000, v151
	v_pk_mul_f32 v[230:231], v[230:231], v[184:185]
	v_cvt_pk_bf16_f32 v148, v234, v235
	v_cvt_pk_bf16_f32 v149, v236, v237
	v_cvt_pk_bf16_f32 v150, v228, v229
	v_cvt_pk_bf16_f32 v151, v230, v231
	v_add_u32_e32 v219, 0x5000, v218
	global_store_dwordx4 v219, v[148:151], s[24:25]
	v_add_u32_e32 v219, 14, v212
	v_and_b32_e32 v219, 7, v219
	v_xor_b32_e32 v219, v213, v219
	v_add_u32_e32 v188, 14, v215
	v_lshlrev_b32_e32 v188, 10, v188
	v_lshl_add_u32 v219, v219, 4, v188
	v_xor_b32_e32 v188, 16, v219
	ds_read_b128 v[234:237], v219
	ds_read_b128 v[228:231], v188
	s_waitcnt vmcnt(7)
	s_waitcnt lgkmcnt(2)
	v_lshlrev_b32_e32 v184, 16, v152
	v_and_b32_e32 v185, 0xffff0000, v152
	v_pk_mul_f32 v[244:245], v[244:245], v[184:185]
	v_lshlrev_b32_e32 v184, 16, v153
	v_and_b32_e32 v185, 0xffff0000, v153
	v_pk_mul_f32 v[246:247], v[246:247], v[184:185]
	v_lshlrev_b32_e32 v184, 16, v154
	v_and_b32_e32 v185, 0xffff0000, v154
	v_pk_mul_f32 v[220:221], v[220:221], v[184:185]
	v_lshlrev_b32_e32 v184, 16, v155
	v_and_b32_e32 v185, 0xffff0000, v155
	v_pk_mul_f32 v[222:223], v[222:223], v[184:185]
	v_cvt_pk_bf16_f32 v152, v244, v245
	v_cvt_pk_bf16_f32 v153, v246, v247
	v_cvt_pk_bf16_f32 v154, v220, v221
	v_cvt_pk_bf16_f32 v155, v222, v223
	v_add_u32_e32 v219, 0x6000, v218
	global_store_dwordx4 v219, v[152:155], s[24:25]
	s_waitcnt vmcnt(7)
	s_waitcnt lgkmcnt(0)
	v_lshlrev_b32_e32 v184, 16, v156
	v_and_b32_e32 v185, 0xffff0000, v156
	v_pk_mul_f32 v[234:235], v[234:235], v[184:185]
	v_lshlrev_b32_e32 v184, 16, v157
	v_and_b32_e32 v185, 0xffff0000, v157
	v_pk_mul_f32 v[236:237], v[236:237], v[184:185]
	v_lshlrev_b32_e32 v184, 16, v158
	v_and_b32_e32 v185, 0xffff0000, v158
	v_pk_mul_f32 v[228:229], v[228:229], v[184:185]
	v_lshlrev_b32_e32 v184, 16, v159
	v_and_b32_e32 v185, 0xffff0000, v159
	v_pk_mul_f32 v[230:231], v[230:231], v[184:185]
	v_cvt_pk_bf16_f32 v156, v234, v235
	v_cvt_pk_bf16_f32 v157, v236, v237
	v_cvt_pk_bf16_f32 v158, v228, v229
	v_cvt_pk_bf16_f32 v159, v230, v231
	v_add_u32_e32 v219, 0x7000, v218
	global_store_dwordx4 v219, v[156:159], s[24:25]
	s_mov_b64 s[6:7], -1
	s_and_b64 vcc, exec, s[14:15]
	s_cbranch_vccnz .LBB0_1046
	s_andn2_b64 vcc, exec, s[20:21]
	s_cbranch_vccnz .LBB0_1045
	s_barrier
	s_branch .LBB0_1045

; #define EPI_FOR(u) \
;     _Pragma("unroll") for (int ai = 0; ai < 2; ++ai) _Pragma("unroll") for (int m = 0; m < 4; ++m) _Pragma("unroll") for (int bj = 0; bj < 2; ++bj)
; #define EPI_COL(u) (EPI_CB(u) + 8 * fq)
;     DI void operator()(const Acc& acc, const Unit& u, int wr, int wc, int fr, int fq) const {
;         EPI_FOR(u) {
;             const int row = EPI_ROW(u), col = EPI_COL(u); EPI_V(v);
;             const u32x4 gg = *(const u32x4*)(gate + (size_t)row * 3072 + gi * 1024 + col);
;             const float gf[8] = {bflo(gg.x), bfhi(gg.x), bflo(gg.y), bfhi(gg.y), bflo(gg.z), bfhi(gg.z), bflo(gg.w), bfhi(gg.w)};
;             bf16_t* mp = mrg + (size_t)row * 1024 + col;
;             if (accum) {
.LBB0_1222:
	s_lshl_b32 s2, s44, 8
	s_lshl_b32 s6, s28, 8
	v_readfirstlane_b32 s7, v232
	s_lshr_b32 s7, s7, 6
	s_lshl_b32 s7, s7, 4
	v_add_u32_e32 v210, s64, v145
	v_lshlrev_b32_e32 v210, 10, v210
	v_and_b32_e32 v211, 7, v145
	v_lshlrev_b32_e32 v212, 1, v144
	v_xor_b32_e32 v211, v212, v211
	v_lshl_add_u32 v210, v211, 4, v210
	s_lshl_b32 s8, s65, 2
	v_add_u32_e32 v210, s8, v210
	v_xor_b32_e32 v211, 16, v210
	v_lshrrev_b32_e32 v212, 5, v233
	v_and_b32_e32 v213, 31, v233
	v_lshl_add_u32 v214, v213, 3, s6
	v_lshlrev_b32_e32 v214, 1, v214
	v_lshlrev_b32_e32 v213, 1, v213

; #define EPI_FOR(u) \
;     _Pragma("unroll") for (int ai = 0; ai < 2; ++ai) _Pragma("unroll") for (int m = 0; m < 4; ++m) _Pragma("unroll") for (int bj = 0; bj < 2; ++bj)
; #define EPI_COL(u) (EPI_CB(u) + 8 * fq)
; DI u32x4 pack8(const float* v) { u32x4 w; w.x = pk2(v[0], v[1]); w.y = pk2(v[2], v[3]); w.z = pk2(v[4], v[5]); w.w = pk2(v[6], v[7]); return w; }
;     DI void operator()(const Acc& acc, const Unit& u, int wr, int wc, int fr, int fq) const {
;         EPI_FOR(u) {
;             const int row = EPI_ROW(u), col = EPI_COL(u); EPI_V(v);
;             const u32x4 gg = *(const u32x4*)(gate + (size_t)row * 3072 + gi * 1024 + col);
;             const float gf[8] = {bflo(gg.x), bfhi(gg.x), bflo(gg.y), bfhi(gg.y), bflo(gg.z), bfhi(gg.z), bflo(gg.w), bfhi(gg.w)};
;             bf16_t* mp = mrg + (size_t)row * 1024 + col;
;             if (accum) {
;                 const u32x4 oo = *(const u32x4*)mp;
;                 const float of[8] = {bflo(oo.x), bfhi(oo.x), bflo(oo.y), bfhi(oo.y), bflo(oo.z), bfhi(oo.z), bflo(oo.w), bfhi(oo.w)};
; #pragma unroll
;                 for (int j = 0; j < 8; ++j) v[j] = of[j] + gf[j] * v[j];
;             } else {
; #pragma unroll
;                 for (int j = 0; j < 8; ++j) v[j] = gf[j] * v[j];
;             }
;             *(u32x4*)mp = pack8(v);
;         }
	v_add_u32_e32 v215, s7, v212
	s_add_i32 s8, s2, 0
	v_add_u32_e32 v216, s8, v215
	v_mul_u32_u24_e32 v217, 0x1800, v216
	v_add_u32_e32 v217, v217, v214
	v_add_u32_e32 v217, 0x1000, v217
	v_lshl_add_u32 v218, v216, 11, v214
	global_load_dwordx4 v[128:131], v217, s[20:21]
	global_load_dwordx4 v[160:163], v218, s[22:23]
	v_add_u32_e32 v219, 0x3000, v217
	global_load_dwordx4 v[132:135], v219, s[20:21]
	v_add_u32_e32 v219, 0x1000, v218
	global_load_dwordx4 v[164:167], v219, s[22:23]
	v_add_u32_e32 v219, 0x6000, v217
	global_load_dwordx4 v[136:139], v219, s[20:21]
	v_add_u32_e32 v219, 0x2000, v218
	global_load_dwordx4 v[168:171], v219, s[22:23]
	v_add_u32_e32 v219, 0x9000, v217
	global_load_dwordx4 v[140:143], v219, s[20:21]
	v_add_u32_e32 v219, 0x3000, v218
	global_load_dwordx4 v[172:175], v219, s[22:23]
	v_add_u32_e32 v219, 0xc000, v217
	global_load_dwordx4 v[144:147], v219, s[20:21]
	v_add_u32_e32 v219, 0x4000, v218
	global_load_dwordx4 v[176:179], v219, s[22:23]
	v_add_u32_e32 v219, 0xf000, v217
	global_load_dwordx4 v[148:151], v219, s[20:21]
	v_add_u32_e32 v219, 0x5000, v218
	global_load_dwordx4 v[180:183], v219, s[22:23]
	v_add_u32_e32 v219, 0x12000, v217
	global_load_dwordx4 v[152:155], v219, s[20:21]
	v_add_u32_e32 v219, 0x6000, v218
	global_load_dwordx4 v[224:227], v219, s[22:23]
	v_add_u32_e32 v219, 0x15000, v217
	global_load_dwordx4 v[156:159], v219, s[20:21]
	v_add_u32_e32 v219, 0x7000, v218
	global_load_dwordx4 v[240:243], v219, s[22:23]
	s_waitcnt vmcnt(16)
	s_barrier
	ds_write_b128 v210, v[124:127]
	ds_write_b128 v211, v[120:123]
	ds_write_b128 v210, v[116:119] offset:512
	ds_write_b128 v211, v[112:115] offset:512
	ds_write_b128 v210, v[108:111] offset:16384
	ds_write_b128 v211, v[104:107] offset:16384
	ds_write_b128 v210, v[100:103] offset:16896
	ds_write_b128 v211, v[96:99] offset:16896
	ds_write_b128 v210, v[92:95] offset:32768
	ds_write_b128 v211, v[88:91] offset:32768
	ds_write_b128 v210, v[84:87] offset:33280
	ds_write_b128 v211, v[80:83] offset:33280
	ds_write_b128 v210, v[76:79] offset:49152
	ds_write_b128 v211, v[72:75] offset:49152
	ds_write_b128 v210, v[68:71] offset:49664
	ds_write_b128 v211, v[64:67] offset:49664
	s_waitcnt lgkmcnt(0)
	s_barrier
	v_add_u32_e32 v219, 0, v212
	v_and_b32_e32 v219, 7, v219
	v_xor_b32_e32 v219, v213, v219
	v_add_u32_e32 v188, 0, v215
	v_lshlrev_b32_e32 v188, 10, v188
	v_lshl_add_u32 v219, v219, 4, v188
	v_xor_b32_e32 v188, 16, v219
	ds_read_b128 v[244:247], v219
	ds_read_b128 v[220:223], v188
	v_add_u32_e32 v219, 2, v212
	v_and_b32_e32 v219, 7, v219
	v_xor_b32_e32 v219, v213, v219
	v_add_u32_e32 v188, 2, v215
	v_lshlrev_b32_e32 v188, 10, v188
	v_lshl_add_u32 v219, v219, 4, v188
	v_xor_b32_e32 v188, 16, v219
	ds_read_b128 v[234:237], v219
	ds_read_b128 v[228:231], v188
	s_waitcnt vmcnt(14)
	s_waitcnt lgkmcnt(2)
	v_lshlrev_b32_e32 v184, 16, v128
	v_and_b32_e32 v185, 0xffff0000, v128
	v_lshlrev_b32_e32 v186, 16, v160
	v_and_b32_e32 v187, 0xffff0000, v160
	v_pk_fma_f32 v[244:245], v[244:245], v[184:185], v[186:187]
	v_lshlrev_b32_e32 v184, 16, v129
	v_and_b32_e32 v185, 0xffff0000, v129
	v_lshlrev_b32_e32 v186, 16, v161
	v_and_b32_e32 v187, 0xffff0000, v161
	v_pk_fma_f32 v[246:247], v[246:247], v[184:185], v[186:187]
	v_lshlrev_b32_e32 v184, 16, v130
	v_and_b32_e32 v185, 0xffff0000, v130
	v_lshlrev_b32_e32 v186, 16, v162
	v_and_b32_e32 v187, 0xffff0000, v162
	v_pk_fma_f32 v[220:221], v[220:221], v[184:185], v[186:187]
	v_lshlrev_b32_e32 v184, 16, v131
	v_and_b32_e32 v185, 0xffff0000, v131
	v_lshlrev_b32_e32 v186, 16, v163
	v_and_b32_e32 v187, 0xffff0000, v163
	v_pk_fma_f32 v[222:223], v[222:223], v[184:185], v[186:187]
	v_cvt_pk_bf16_f32 v128, v244, v245
	v_cvt_pk_bf16_f32 v129, v246, v247
	v_cvt_pk_bf16_f32 v130, v220, v221
	v_cvt_pk_bf16_f32 v131, v222, v223
	global_store_dwordx4 v218, v[128:131], s[22:23]
	v_add_u32_e32 v219, 4, v212
	v_and_b32_e32 v219, 7, v219
	v_xor_b32_e32 v219, v213, v219
	v_add_u32_e32 v188, 4, v215
	v_lshlrev_b32_e32 v188, 10, v188
	v_lshl_add_u32 v219, v219, 4, v188
	v_xor_b32_e32 v188, 16, v219
	ds_read_b128 v[244:247], v219
	ds_read_b128 v[220:223], v188
	s_waitcnt vmcnt(13)
	s_waitcnt lgkmcnt(2)
	v_lshlrev_b32_e32 v184, 16, v132
	v_and_b32_e32 v185, 0xffff0000, v132
	v_lshlrev_b32_e32 v186, 16, v164
	v_and_b32_e32 v187, 0xffff0000, v164
	v_pk_fma_f32 v[234:235], v[234:235], v[184:185], v[186:187]
	v_lshlrev_b32_e32 v184, 16, v133
	v_and_b32_e32 v185, 0xffff0000, v133
	v_lshlrev_b32_e32 v186, 16, v165
	v_and_b32_e32 v187, 0xffff0000, v165
	v_pk_fma_f32 v[236:237], v[236:237], v[184:185], v[186:187]
	v_lshlrev_b32_e32 v184, 16, v134
	v_and_b32_e32 v185, 0xffff0000, v134
	v_lshlrev_b32_e32 v186, 16, v166
	v_and_b32_e32 v187, 0xffff0000, v166
	v_pk_fma_f32 v[228:229], v[228:229], v[184:185], v[186:187]
	v_lshlrev_b32_e32 v184, 16, v135
	v_and_b32_e32 v185, 0xffff0000, v135
	v_lshlrev_b32_e32 v186, 16, v167
	v_and_b32_e32 v187, 0xffff0000, v167
	v_pk_fma_f32 v[230:231], v[230:231], v[184:185], v[186:187]
	v_cvt_pk_bf16_f32 v132, v234, v235
	v_cvt_pk_bf16_f32 v133, v236, v237
	v_cvt_pk_bf16_f32 v134, v228, v229
	v_cvt_pk_bf16_f32 v135, v230, v231
	v_add_u32_e32 v219, 0x1000, v218
	global_store_dwordx4 v219, v[132:135], s[22:23]
	v_add_u32_e32 v219, 6, v212
	v_and_b32_e32 v219, 7, v219
	v_xor_b32_e32 v219, v213, v219
	v_add_u32_e32 v188, 6, v215
	v_lshlrev_b32_e32 v188, 10, v188
	v_lshl_add_u32 v219, v219, 4, v188
	v_xor_b32_e32 v188, 16, v219
	ds_read_b128 v[234:237], v219
	ds_read_b128 v[228:231], v188
	s_waitcnt vmcnt(12)
	s_waitcnt lgkmcnt(2)
; #define EPI_FOR(u) \
;     _Pragma("unroll") for (int ai = 0; ai < 2; ++ai) _Pragma("unroll") for (int m = 0; m < 4; ++m) _Pragma("unroll") for (int bj = 0; bj < 2; ++bj)
; #define EPI_COL(u) (EPI_CB(u) + 8 * fq)
; DI u32x4 pack8(const float* v) { u32x4 w; w.x = pk2(v[0], v[1]); w.y = pk2(v[2], v[3]); w.z = pk2(v[4], v[5]); w.w = pk2(v[6], v[7]); return w; }
;     DI void operator()(const Acc& acc, const Unit& u, int wr, int wc, int fr, int fq) const {
;         EPI_FOR(u) {
;             const int row = EPI_ROW(u), col = EPI_COL(u); EPI_V(v);
;             const u32x4 gg = *(const u32x4*)(gate + (size_t)row * 3072 + gi * 1024 + col);
;             const float gf[8] = {bflo(gg.x), bfhi(gg.x), bflo(gg.y), bfhi(gg.y), bflo(gg.z), bfhi(gg.z), bflo(gg.w), bfhi(gg.w)};
;             bf16_t* mp = mrg + (size_t)row * 1024 + col;
;             if (accum) {
;                 const u32x4 oo = *(const u32x4*)mp;
;                 const float of[8] = {bflo(oo.x), bfhi(oo.x), bflo(oo.y), bfhi(oo.y), bflo(oo.z), bfhi(oo.z), bflo(oo.w), bfhi(oo.w)};
; #pragma unroll
;                 for (int j = 0; j < 8; ++j) v[j] = of[j] + gf[j] * v[j];
;             } else {
; #pragma unroll
;                 for (int j = 0; j < 8; ++j) v[j] = gf[j] * v[j];
;             }
;             *(u32x4*)mp = pack8(v);
;         }
	v_lshlrev_b32_e32 v184, 16, v136
	v_and_b32_e32 v185, 0xffff0000, v136
	v_lshlrev_b32_e32 v186, 16, v168
	v_and_b32_e32 v187, 0xffff0000, v168
	v_pk_fma_f32 v[244:245], v[244:245], v[184:185], v[186:187]
	v_lshlrev_b32_e32 v184, 16, v137
	v_and_b32_e32 v185, 0xffff0000, v137
	v_lshlrev_b32_e32 v186, 16, v169
	v_and_b32_e32 v187, 0xffff0000, v169
	v_pk_fma_f32 v[246:247], v[246:247], v[184:185], v[186:187]
	v_lshlrev_b32_e32 v184, 16, v138
	v_and_b32_e32 v185, 0xffff0000, v138
	v_lshlrev_b32_e32 v186, 16, v170
	v_and_b32_e32 v187, 0xffff0000, v170
	v_pk_fma_f32 v[220:221], v[220:221], v[184:185], v[186:187]
	v_lshlrev_b32_e32 v184, 16, v139
	v_and_b32_e32 v185, 0xffff0000, v139
	v_lshlrev_b32_e32 v186, 16, v171
	v_and_b32_e32 v187, 0xffff0000, v171
	v_pk_fma_f32 v[222:223], v[222:223], v[184:185], v[186:187]
	v_cvt_pk_bf16_f32 v136, v244, v245
	v_cvt_pk_bf16_f32 v137, v246, v247
	v_cvt_pk_bf16_f32 v138, v220, v221
	v_cvt_pk_bf16_f32 v139, v222, v223
	v_add_u32_e32 v219, 0x2000, v218
	global_store_dwordx4 v219, v[136:139], s[22:23]
	v_add_u32_e32 v219, 8, v212
	v_and_b32_e32 v219, 7, v219
	v_xor_b32_e32 v219, v213, v219
	v_add_u32_e32 v188, 8, v215
	v_lshlrev_b32_e32 v188, 10, v188
	v_lshl_add_u32 v219, v219, 4, v188
	v_xor_b32_e32 v188, 16, v219
	ds_read_b128 v[244:247], v219
	ds_read_b128 v[220:223], v188
	s_waitcnt vmcnt(11)
	s_waitcnt lgkmcnt(2)
	v_lshlrev_b32_e32 v184, 16, v140
	v_and_b32_e32 v185, 0xffff0000, v140
	v_lshlrev_b32_e32 v186, 16, v172
	v_and_b32_e32 v187, 0xffff0000, v172
	v_pk_fma_f32 v[234:235], v[234:235], v[184:185], v[186:187]
	v_lshlrev_b32_e32 v184, 16, v141
	v_and_b32_e32 v185, 0xffff0000, v141
	v_lshlrev_b32_e32 v186, 16, v173
	v_and_b32_e32 v187, 0xffff0000, v173
	v_pk_fma_f32 v[236:237], v[236:237], v[184:185], v[186:187]
	v_lshlrev_b32_e32 v184, 16, v142
	v_and_b32_e32 v185, 0xffff0000, v142
	v_lshlrev_b32_e32 v186, 16, v174
	v_and_b32_e32 v187, 0xffff0000, v174
	v_pk_fma_f32 v[228:229], v[228:229], v[184:185], v[186:187]
	v_lshlrev_b32_e32 v184, 16, v143
	v_and_b32_e32 v185, 0xffff0000, v143
	v_lshlrev_b32_e32 v186, 16, v175
	v_and_b32_e32 v187, 0xffff0000, v175
	v_pk_fma_f32 v[230:231], v[230:231], v[184:185], v[186:187]
	v_cvt_pk_bf16_f32 v140, v234, v235
	v_cvt_pk_bf16_f32 v141, v236, v237
	v_cvt_pk_bf16_f32 v142, v228, v229
	v_cvt_pk_bf16_f32 v143, v230, v231
	v_add_u32_e32 v219, 0x3000, v218
	global_store_dwordx4 v219, v[140:143], s[22:23]
	v_add_u32_e32 v219, 10, v212
	v_and_b32_e32 v219, 7, v219
	v_xor_b32_e32 v219, v213, v219
	v_add_u32_e32 v188, 10, v215
	v_lshlrev_b32_e32 v188, 10, v188
	v_lshl_add_u32 v219, v219, 4, v188
	v_xor_b32_e32 v188, 16, v219
	ds_read_b128 v[234:237], v219
	ds_read_b128 v[228:231], v188
	s_waitcnt vmcnt(10)
	s_waitcnt lgkmcnt(2)
	v_lshlrev_b32_e32 v184, 16, v144
	v_and_b32_e32 v185, 0xffff0000, v144
	v_lshlrev_b32_e32 v186, 16, v176
	v_and_b32_e32 v187, 0xffff0000, v176
	v_pk_fma_f32 v[244:245], v[244:245], v[184:185], v[186:187]
	v_lshlrev_b32_e32 v184, 16, v145
	v_and_b32_e32 v185, 0xffff0000, v145
	v_lshlrev_b32_e32 v186, 16, v177
	v_and_b32_e32 v187, 0xffff0000, v177
	v_pk_fma_f32 v[246:247], v[246:247], v[184:185], v[186:187]
	v_lshlrev_b32_e32 v184, 16, v146
	v_and_b32_e32 v185, 0xffff0000, v146
	v_lshlrev_b32_e32 v186, 16, v178
	v_and_b32_e32 v187, 0xffff0000, v178
	v_pk_fma_f32 v[220:221], v[220:221], v[184:185], v[186:187]
	v_lshlrev_b32_e32 v184, 16, v147
	v_and_b32_e32 v185, 0xffff0000, v147
	v_lshlrev_b32_e32 v186, 16, v179
	v_and_b32_e32 v187, 0xffff0000, v179
	v_pk_fma_f32 v[222:223], v[222:223], v[184:185], v[186:187]
	v_cvt_pk_bf16_f32 v144, v244, v245
	v_cvt_pk_bf16_f32 v145, v246, v247
	v_cvt_pk_bf16_f32 v146, v220, v221
	v_cvt_pk_bf16_f32 v147, v222, v223
	v_add_u32_e32 v219, 0x4000, v218
	global_store_dwordx4 v219, v[144:147], s[22:23]
	v_add_u32_e32 v219, 12, v212
	v_and_b32_e32 v219, 7, v219
	v_xor_b32_e32 v219, v213, v219
	v_add_u32_e32 v188, 12, v215
	v_lshlrev_b32_e32 v188, 10, v188
	v_lshl_add_u32 v219, v219, 4, v188
	v_xor_b32_e32 v188, 16, v219
	ds_read_b128 v[244:247], v219
	ds_read_b128 v[220:223], v188
	s_waitcnt vmcnt(9)
	s_waitcnt lgkmcnt(2)
	v_lshlrev_b32_e32 v184, 16, v148
	v_and_b32_e32 v185, 0xffff0000, v148
	v_lshlrev_b32_e32 v186, 16, v180
	v_and_b32_e32 v187, 0xffff0000, v180
	v_pk_fma_f32 v[234:235], v[234:235], v[184:185], v[186:187]
	v_lshlrev_b32_e32 v184, 16, v149
	v_and_b32_e32 v185, 0xffff0000, v149
	v_lshlrev_b32_e32 v186, 16, v181
	v_and_b32_e32 v187, 0xffff0000, v181
	v_pk_fma_f32 v[236:237], v[236:237], v[184:185], v[186:187]
	v_lshlrev_b32_e32 v184, 16, v150
	v_and_b32_e32 v185, 0xffff0000, v150
	v_lshlrev_b32_e32 v186, 16, v182
	v_and_b32_e32 v187, 0xffff0000, v182
	v_pk_fma_f32 v[228:229], v[228:229], v[184:185], v[186:187]
	v_lshlrev_b32_e32 v184, 16, v151
	v_and_b32_e32 v185, 0xffff0000, v151
	v_lshlrev_b32_e32 v186, 16, v183
	v_and_b32_e32 v187, 0xffff0000, v183
	v_pk_fma_f32 v[230:231], v[230:231], v[184:185], v[186:187]
	v_cvt_pk_bf16_f32 v148, v234, v235
	v_cvt_pk_bf16_f32 v149, v236, v237
	v_cvt_pk_bf16_f32 v150, v228, v229
	v_cvt_pk_bf16_f32 v151, v230, v231
	v_add_u32_e32 v219, 0x5000, v218
	global_store_dwordx4 v219, v[148:151], s[22:23]
	v_add_u32_e32 v219, 14, v212
	v_and_b32_e32 v219, 7, v219
	v_xor_b32_e32 v219, v213, v219
	v_add_u32_e32 v188, 14, v215
	v_lshlrev_b32_e32 v188, 10, v188
	v_lshl_add_u32 v219, v219, 4, v188
	v_xor_b32_e32 v188, 16, v219
	ds_read_b128 v[234:237], v219
	ds_read_b128 v[228:231], v188
	s_waitcnt vmcnt(8)
	s_waitcnt lgkmcnt(2)
; #define EPI_FOR(u) \
;     _Pragma("unroll") for (int ai = 0; ai < 2; ++ai) _Pragma("unroll") for (int m = 0; m < 4; ++m) _Pragma("unroll") for (int bj = 0; bj < 2; ++bj)
; #define EPI_COL(u) (EPI_CB(u) + 8 * fq)
; DI u32x4 pack8(const float* v) { u32x4 w; w.x = pk2(v[0], v[1]); w.y = pk2(v[2], v[3]); w.z = pk2(v[4], v[5]); w.w = pk2(v[6], v[7]); return w; }
;     DI void operator()(const Acc& acc, const Unit& u, int wr, int wc, int fr, int fq) const {
;         EPI_FOR(u) {
;             const int row = EPI_ROW(u), col = EPI_COL(u); EPI_V(v);
;             const u32x4 gg = *(const u32x4*)(gate + (size_t)row * 3072 + gi * 1024 + col);
;             const float gf[8] = {bflo(gg.x), bfhi(gg.x), bflo(gg.y), bfhi(gg.y), bflo(gg.z), bfhi(gg.z), bflo(gg.w), bfhi(gg.w)};
;             bf16_t* mp = mrg + (size_t)row * 1024 + col;
;             if (accum) {
;                 const u32x4 oo = *(const u32x4*)mp;
;                 const float of[8] = {bflo(oo.x), bfhi(oo.x), bflo(oo.y), bfhi(oo.y), bflo(oo.z), bfhi(oo.z), bflo(oo.w), bfhi(oo.w)};
; #pragma unroll
;                 for (int j = 0; j < 8; ++j) v[j] = of[j] + gf[j] * v[j];
;             } else {
; #pragma unroll
;                 for (int j = 0; j < 8; ++j) v[j] = gf[j] * v[j];
;             }
;             *(u32x4*)mp = pack8(v);
;         }
	v_lshlrev_b32_e32 v184, 16, v152
	v_and_b32_e32 v185, 0xffff0000, v152
	v_lshlrev_b32_e32 v186, 16, v224
	v_and_b32_e32 v187, 0xffff0000, v224
	v_pk_fma_f32 v[244:245], v[244:245], v[184:185], v[186:187]
	v_lshlrev_b32_e32 v184, 16, v153
	v_and_b32_e32 v185, 0xffff0000, v153
	v_lshlrev_b32_e32 v186, 16, v225
	v_and_b32_e32 v187, 0xffff0000, v225
	v_pk_fma_f32 v[246:247], v[246:247], v[184:185], v[186:187]
	v_lshlrev_b32_e32 v184, 16, v154
	v_and_b32_e32 v185, 0xffff0000, v154
	v_lshlrev_b32_e32 v186, 16, v226
	v_and_b32_e32 v187, 0xffff0000, v226
	v_pk_fma_f32 v[220:221], v[220:221], v[184:185], v[186:187]
	v_lshlrev_b32_e32 v184, 16, v155
	v_and_b32_e32 v185, 0xffff0000, v155
	v_lshlrev_b32_e32 v186, 16, v227
	v_and_b32_e32 v187, 0xffff0000, v227
	v_pk_fma_f32 v[222:223], v[222:223], v[184:185], v[186:187]
	v_cvt_pk_bf16_f32 v152, v244, v245
	v_cvt_pk_bf16_f32 v153, v246, v247
	v_cvt_pk_bf16_f32 v154, v220, v221
	v_cvt_pk_bf16_f32 v155, v222, v223
	v_add_u32_e32 v219, 0x6000, v218
	global_store_dwordx4 v219, v[152:155], s[22:23]
	s_waitcnt vmcnt(7)
	s_waitcnt lgkmcnt(0)
	v_lshlrev_b32_e32 v184, 16, v156
	v_and_b32_e32 v185, 0xffff0000, v156
	v_lshlrev_b32_e32 v186, 16, v240
	v_and_b32_e32 v187, 0xffff0000, v240
	v_pk_fma_f32 v[234:235], v[234:235], v[184:185], v[186:187]
	v_lshlrev_b32_e32 v184, 16, v157
	v_and_b32_e32 v185, 0xffff0000, v157
	v_lshlrev_b32_e32 v186, 16, v241
	v_and_b32_e32 v187, 0xffff0000, v241
	v_pk_fma_f32 v[236:237], v[236:237], v[184:185], v[186:187]
	v_lshlrev_b32_e32 v184, 16, v158
	v_and_b32_e32 v185, 0xffff0000, v158
	v_lshlrev_b32_e32 v186, 16, v242
	v_and_b32_e32 v187, 0xffff0000, v242
	v_pk_fma_f32 v[228:229], v[228:229], v[184:185], v[186:187]
	v_lshlrev_b32_e32 v184, 16, v159
	v_and_b32_e32 v185, 0xffff0000, v159
	v_lshlrev_b32_e32 v186, 16, v243
	v_and_b32_e32 v187, 0xffff0000, v243
	v_pk_fma_f32 v[230:231], v[230:231], v[184:185], v[186:187]
	v_cvt_pk_bf16_f32 v156, v234, v235
	v_cvt_pk_bf16_f32 v157, v236, v237
	v_cvt_pk_bf16_f32 v158, v228, v229
	v_cvt_pk_bf16_f32 v159, v230, v231
	v_add_u32_e32 v219, 0x7000, v218
	global_store_dwordx4 v219, v[156:159], s[22:23]
	v_add_u32_e32 v215, s7, v212
	s_add_i32 s8, s2, 128
	v_add_u32_e32 v216, s8, v215
	v_mul_u32_u24_e32 v217, 0x1800, v216
	v_add_u32_e32 v217, v217, v214
	v_add_u32_e32 v217, 0x1000, v217
	v_lshl_add_u32 v218, v216, 11, v214
	global_load_dwordx4 v[128:131], v217, s[20:21]
	global_load_dwordx4 v[160:163], v218, s[22:23]
	v_add_u32_e32 v219, 0x3000, v217
	global_load_dwordx4 v[132:135], v219, s[20:21]
	v_add_u32_e32 v219, 0x1000, v218
	global_load_dwordx4 v[164:167], v219, s[22:23]
	v_add_u32_e32 v219, 0x6000, v217
	global_load_dwordx4 v[136:139], v219, s[20:21]
	v_add_u32_e32 v219, 0x2000, v218
	global_load_dwordx4 v[168:171], v219, s[22:23]
	v_add_u32_e32 v219, 0x9000, v217
	global_load_dwordx4 v[140:143], v219, s[20:21]
	v_add_u32_e32 v219, 0x3000, v218
	global_load_dwordx4 v[172:175], v219, s[22:23]
	v_add_u32_e32 v219, 0xc000, v217
	global_load_dwordx4 v[144:147], v219, s[20:21]
	v_add_u32_e32 v219, 0x4000, v218
	global_load_dwordx4 v[176:179], v219, s[22:23]
	v_add_u32_e32 v219, 0xf000, v217
	global_load_dwordx4 v[148:151], v219, s[20:21]
	v_add_u32_e32 v219, 0x5000, v218
	global_load_dwordx4 v[180:183], v219, s[22:23]
	v_add_u32_e32 v219, 0x12000, v217
	global_load_dwordx4 v[152:155], v219, s[20:21]
	v_add_u32_e32 v219, 0x6000, v218
	global_load_dwordx4 v[224:227], v219, s[22:23]
	v_add_u32_e32 v219, 0x15000, v217
	global_load_dwordx4 v[156:159], v219, s[20:21]
	v_add_u32_e32 v219, 0x7000, v218
	global_load_dwordx4 v[240:243], v219, s[22:23]
	s_barrier
	ds_write_b128 v210, v[60:63]
	ds_write_b128 v211, v[56:59]
	ds_write_b128 v210, v[52:55] offset:512
	ds_write_b128 v211, v[48:51] offset:512
	ds_write_b128 v210, v[44:47] offset:16384
	ds_write_b128 v211, v[40:43] offset:16384
	ds_write_b128 v210, v[36:39] offset:16896
	ds_write_b128 v211, v[32:35] offset:16896
	ds_write_b128 v210, v[28:31] offset:32768
	ds_write_b128 v211, v[24:27] offset:32768
	ds_write_b128 v210, v[20:23] offset:33280
	ds_write_b128 v211, v[16:19] offset:33280
	ds_write_b128 v210, v[12:15] offset:49152
	ds_write_b128 v211, v[8:11] offset:49152
	ds_write_b128 v210, v[4:7] offset:49664
	ds_write_b128 v211, v[0:3] offset:49664
	s_waitcnt lgkmcnt(0)
	s_barrier
; #define EPI_FOR(u) \
;     _Pragma("unroll") for (int ai = 0; ai < 2; ++ai) _Pragma("unroll") for (int m = 0; m < 4; ++m) _Pragma("unroll") for (int bj = 0; bj < 2; ++bj)
; #define EPI_COL(u) (EPI_CB(u) + 8 * fq)
; DI u32x4 pack8(const float* v) { u32x4 w; w.x = pk2(v[0], v[1]); w.y = pk2(v[2], v[3]); w.z = pk2(v[4], v[5]); w.w = pk2(v[6], v[7]); return w; }
;     DI void operator()(const Acc& acc, const Unit& u, int wr, int wc, int fr, int fq) const {
;         EPI_FOR(u) {
;             const int row = EPI_ROW(u), col = EPI_COL(u); EPI_V(v);
;             const u32x4 gg = *(const u32x4*)(gate + (size_t)row * 3072 + gi * 1024 + col);
;             const float gf[8] = {bflo(gg.x), bfhi(gg.x), bflo(gg.y), bfhi(gg.y), bflo(gg.z), bfhi(gg.z), bflo(gg.w), bfhi(gg.w)};
;             bf16_t* mp = mrg + (size_t)row * 1024 + col;
;             if (accum) {
;                 const u32x4 oo = *(const u32x4*)mp;
;                 const float of[8] = {bflo(oo.x), bfhi(oo.x), bflo(oo.y), bfhi(oo.y), bflo(oo.z), bfhi(oo.z), bflo(oo.w), bfhi(oo.w)};
; #pragma unroll
;                 for (int j = 0; j < 8; ++j) v[j] = of[j] + gf[j] * v[j];
;             } else {
; #pragma unroll
;                 for (int j = 0; j < 8; ++j) v[j] = gf[j] * v[j];
;             }
;             *(u32x4*)mp = pack8(v);
;         }
	v_add_u32_e32 v219, 0, v212
	v_and_b32_e32 v219, 7, v219
	v_xor_b32_e32 v219, v213, v219
	v_add_u32_e32 v188, 0, v215
	v_lshlrev_b32_e32 v188, 10, v188
	v_lshl_add_u32 v219, v219, 4, v188
	v_xor_b32_e32 v188, 16, v219
	ds_read_b128 v[244:247], v219
	ds_read_b128 v[220:223], v188
	v_add_u32_e32 v219, 2, v212
	v_and_b32_e32 v219, 7, v219
	v_xor_b32_e32 v219, v213, v219
	v_add_u32_e32 v188, 2, v215
	v_lshlrev_b32_e32 v188, 10, v188
	v_lshl_add_u32 v219, v219, 4, v188
	v_xor_b32_e32 v188, 16, v219
	ds_read_b128 v[234:237], v219
	ds_read_b128 v[228:231], v188
	s_waitcnt vmcnt(14)
	s_waitcnt lgkmcnt(2)
	v_lshlrev_b32_e32 v184, 16, v128
	v_and_b32_e32 v185, 0xffff0000, v128
	v_lshlrev_b32_e32 v186, 16, v160
	v_and_b32_e32 v187, 0xffff0000, v160
	v_pk_fma_f32 v[244:245], v[244:245], v[184:185], v[186:187]
	v_lshlrev_b32_e32 v184, 16, v129
	v_and_b32_e32 v185, 0xffff0000, v129
	v_lshlrev_b32_e32 v186, 16, v161
	v_and_b32_e32 v187, 0xffff0000, v161
	v_pk_fma_f32 v[246:247], v[246:247], v[184:185], v[186:187]
	v_lshlrev_b32_e32 v184, 16, v130
	v_and_b32_e32 v185, 0xffff0000, v130
	v_lshlrev_b32_e32 v186, 16, v162
	v_and_b32_e32 v187, 0xffff0000, v162
	v_pk_fma_f32 v[220:221], v[220:221], v[184:185], v[186:187]
	v_lshlrev_b32_e32 v184, 16, v131
	v_and_b32_e32 v185, 0xffff0000, v131
	v_lshlrev_b32_e32 v186, 16, v163
	v_and_b32_e32 v187, 0xffff0000, v163
	v_pk_fma_f32 v[222:223], v[222:223], v[184:185], v[186:187]
	v_cvt_pk_bf16_f32 v128, v244, v245
	v_cvt_pk_bf16_f32 v129, v246, v247
	v_cvt_pk_bf16_f32 v130, v220, v221
	v_cvt_pk_bf16_f32 v131, v222, v223
	global_store_dwordx4 v218, v[128:131], s[22:23]
	v_add_u32_e32 v219, 4, v212
	v_and_b32_e32 v219, 7, v219
	v_xor_b32_e32 v219, v213, v219
	v_add_u32_e32 v188, 4, v215
	v_lshlrev_b32_e32 v188, 10, v188
	v_lshl_add_u32 v219, v219, 4, v188
	v_xor_b32_e32 v188, 16, v219
	ds_read_b128 v[244:247], v219
	ds_read_b128 v[220:223], v188
	s_waitcnt vmcnt(13)
	s_waitcnt lgkmcnt(2)
	v_lshlrev_b32_e32 v184, 16, v132
	v_and_b32_e32 v185, 0xffff0000, v132
	v_lshlrev_b32_e32 v186, 16, v164
	v_and_b32_e32 v187, 0xffff0000, v164
	v_pk_fma_f32 v[234:235], v[234:235], v[184:185], v[186:187]
	v_lshlrev_b32_e32 v184, 16, v133
	v_and_b32_e32 v185, 0xffff0000, v133
	v_lshlrev_b32_e32 v186, 16, v165
	v_and_b32_e32 v187, 0xffff0000, v165
	v_pk_fma_f32 v[236:237], v[236:237], v[184:185], v[186:187]
	v_lshlrev_b32_e32 v184, 16, v134
	v_and_b32_e32 v185, 0xffff0000, v134
	v_lshlrev_b32_e32 v186, 16, v166
	v_and_b32_e32 v187, 0xffff0000, v166
	v_pk_fma_f32 v[228:229], v[228:229], v[184:185], v[186:187]
	v_lshlrev_b32_e32 v184, 16, v135
	v_and_b32_e32 v185, 0xffff0000, v135
	v_lshlrev_b32_e32 v186, 16, v167
	v_and_b32_e32 v187, 0xffff0000, v167
	v_pk_fma_f32 v[230:231], v[230:231], v[184:185], v[186:187]
	v_cvt_pk_bf16_f32 v132, v234, v235
	v_cvt_pk_bf16_f32 v133, v236, v237
	v_cvt_pk_bf16_f32 v134, v228, v229
	v_cvt_pk_bf16_f32 v135, v230, v231
	v_add_u32_e32 v219, 0x1000, v218
	global_store_dwordx4 v219, v[132:135], s[22:23]
	v_add_u32_e32 v219, 6, v212
	v_and_b32_e32 v219, 7, v219
	v_xor_b32_e32 v219, v213, v219
	v_add_u32_e32 v188, 6, v215
	v_lshlrev_b32_e32 v188, 10, v188
	v_lshl_add_u32 v219, v219, 4, v188
	v_xor_b32_e32 v188, 16, v219
	ds_read_b128 v[234:237], v219
	ds_read_b128 v[228:231], v188
	s_waitcnt vmcnt(12)
	s_waitcnt lgkmcnt(2)
	v_lshlrev_b32_e32 v184, 16, v136
	v_and_b32_e32 v185, 0xffff0000, v136
	v_lshlrev_b32_e32 v186, 16, v168
	v_and_b32_e32 v187, 0xffff0000, v168
	v_pk_fma_f32 v[244:245], v[244:245], v[184:185], v[186:187]
	v_lshlrev_b32_e32 v184, 16, v137
	v_and_b32_e32 v185, 0xffff0000, v137
	v_lshlrev_b32_e32 v186, 16, v169
	v_and_b32_e32 v187, 0xffff0000, v169
	v_pk_fma_f32 v[246:247], v[246:247], v[184:185], v[186:187]
	v_lshlrev_b32_e32 v184, 16, v138
	v_and_b32_e32 v185, 0xffff0000, v138
	v_lshlrev_b32_e32 v186, 16, v170
	v_and_b32_e32 v187, 0xffff0000, v170
	v_pk_fma_f32 v[220:221], v[220:221], v[184:185], v[186:187]
	v_lshlrev_b32_e32 v184, 16, v139
	v_and_b32_e32 v185, 0xffff0000, v139
	v_lshlrev_b32_e32 v186, 16, v171
	v_and_b32_e32 v187, 0xffff0000, v171
	v_pk_fma_f32 v[222:223], v[222:223], v[184:185], v[186:187]
	v_cvt_pk_bf16_f32 v136, v244, v245
	v_cvt_pk_bf16_f32 v137, v246, v247
	v_cvt_pk_bf16_f32 v138, v220, v221
	v_cvt_pk_bf16_f32 v139, v222, v223
	v_add_u32_e32 v219, 0x2000, v218
	global_store_dwordx4 v219, v[136:139], s[22:23]
	v_add_u32_e32 v219, 8, v212
	v_and_b32_e32 v219, 7, v219
	v_xor_b32_e32 v219, v213, v219
	v_add_u32_e32 v188, 8, v215
	v_lshlrev_b32_e32 v188, 10, v188
	v_lshl_add_u32 v219, v219, 4, v188
	v_xor_b32_e32 v188, 16, v219
	ds_read_b128 v[244:247], v219
	ds_read_b128 v[220:223], v188
	s_waitcnt vmcnt(11)
	s_waitcnt lgkmcnt(2)
	v_lshlrev_b32_e32 v184, 16, v140
	v_and_b32_e32 v185, 0xffff0000, v140
	v_lshlrev_b32_e32 v186, 16, v172
	v_and_b32_e32 v187, 0xffff0000, v172
	v_pk_fma_f32 v[234:235], v[234:235], v[184:185], v[186:187]
	v_lshlrev_b32_e32 v184, 16, v141
	v_and_b32_e32 v185, 0xffff0000, v141
	v_lshlrev_b32_e32 v186, 16, v173
	v_and_b32_e32 v187, 0xffff0000, v173
	v_pk_fma_f32 v[236:237], v[236:237], v[184:185], v[186:187]
	v_lshlrev_b32_e32 v184, 16, v142
	v_and_b32_e32 v185, 0xffff0000, v142
	v_lshlrev_b32_e32 v186, 16, v174
	v_and_b32_e32 v187, 0xffff0000, v174
	v_pk_fma_f32 v[228:229], v[228:229], v[184:185], v[186:187]
	v_lshlrev_b32_e32 v184, 16, v143
	v_and_b32_e32 v185, 0xffff0000, v143
	v_lshlrev_b32_e32 v186, 16, v175
	v_and_b32_e32 v187, 0xffff0000, v175
	v_pk_fma_f32 v[230:231], v[230:231], v[184:185], v[186:187]
	v_cvt_pk_bf16_f32 v140, v234, v235
	v_cvt_pk_bf16_f32 v141, v236, v237
	v_cvt_pk_bf16_f32 v142, v228, v229
	v_cvt_pk_bf16_f32 v143, v230, v231
	v_add_u32_e32 v219, 0x3000, v218
	global_store_dwordx4 v219, v[140:143], s[22:23]
	v_add_u32_e32 v219, 10, v212
	v_and_b32_e32 v219, 7, v219
	v_xor_b32_e32 v219, v213, v219
	v_add_u32_e32 v188, 10, v215
	v_lshlrev_b32_e32 v188, 10, v188
	v_lshl_add_u32 v219, v219, 4, v188
	v_xor_b32_e32 v188, 16, v219
	ds_read_b128 v[234:237], v219
	ds_read_b128 v[228:231], v188
	s_waitcnt vmcnt(10)
; #define EPI_FOR(u) \
;     _Pragma("unroll") for (int ai = 0; ai < 2; ++ai) _Pragma("unroll") for (int m = 0; m < 4; ++m) _Pragma("unroll") for (int bj = 0; bj < 2; ++bj)
; #define EPI_COL(u) (EPI_CB(u) + 8 * fq)
; DI u32x4 pack8(const float* v) { u32x4 w; w.x = pk2(v[0], v[1]); w.y = pk2(v[2], v[3]); w.z = pk2(v[4], v[5]); w.w = pk2(v[6], v[7]); return w; }
;     DI void operator()(const Acc& acc, const Unit& u, int wr, int wc, int fr, int fq) const {
;         EPI_FOR(u) {
;             const int row = EPI_ROW(u), col = EPI_COL(u); EPI_V(v);
;             const u32x4 gg = *(const u32x4*)(gate + (size_t)row * 3072 + gi * 1024 + col);
;             const float gf[8] = {bflo(gg.x), bfhi(gg.x), bflo(gg.y), bfhi(gg.y), bflo(gg.z), bfhi(gg.z), bflo(gg.w), bfhi(gg.w)};
;             bf16_t* mp = mrg + (size_t)row * 1024 + col;
;             if (accum) {
;                 const u32x4 oo = *(const u32x4*)mp;
;                 const float of[8] = {bflo(oo.x), bfhi(oo.x), bflo(oo.y), bfhi(oo.y), bflo(oo.z), bfhi(oo.z), bflo(oo.w), bfhi(oo.w)};
; #pragma unroll
;                 for (int j = 0; j < 8; ++j) v[j] = of[j] + gf[j] * v[j];
;             } else {
; #pragma unroll
;                 for (int j = 0; j < 8; ++j) v[j] = gf[j] * v[j];
;             }
;             *(u32x4*)mp = pack8(v);
;         }
	s_waitcnt lgkmcnt(2)
	v_lshlrev_b32_e32 v184, 16, v144
	v_and_b32_e32 v185, 0xffff0000, v144
	v_lshlrev_b32_e32 v186, 16, v176
	v_and_b32_e32 v187, 0xffff0000, v176
	v_pk_fma_f32 v[244:245], v[244:245], v[184:185], v[186:187]
	v_lshlrev_b32_e32 v184, 16, v145
	v_and_b32_e32 v185, 0xffff0000, v145
	v_lshlrev_b32_e32 v186, 16, v177
	v_and_b32_e32 v187, 0xffff0000, v177
	v_pk_fma_f32 v[246:247], v[246:247], v[184:185], v[186:187]
	v_lshlrev_b32_e32 v184, 16, v146
	v_and_b32_e32 v185, 0xffff0000, v146
	v_lshlrev_b32_e32 v186, 16, v178
	v_and_b32_e32 v187, 0xffff0000, v178
	v_pk_fma_f32 v[220:221], v[220:221], v[184:185], v[186:187]
	v_lshlrev_b32_e32 v184, 16, v147
	v_and_b32_e32 v185, 0xffff0000, v147
	v_lshlrev_b32_e32 v186, 16, v179
	v_and_b32_e32 v187, 0xffff0000, v179
	v_pk_fma_f32 v[222:223], v[222:223], v[184:185], v[186:187]
	v_cvt_pk_bf16_f32 v144, v244, v245
	v_cvt_pk_bf16_f32 v145, v246, v247
	v_cvt_pk_bf16_f32 v146, v220, v221
	v_cvt_pk_bf16_f32 v147, v222, v223
	v_add_u32_e32 v219, 0x4000, v218
	global_store_dwordx4 v219, v[144:147], s[22:23]
	v_add_u32_e32 v219, 12, v212
	v_and_b32_e32 v219, 7, v219
	v_xor_b32_e32 v219, v213, v219
	v_add_u32_e32 v188, 12, v215
	v_lshlrev_b32_e32 v188, 10, v188
	v_lshl_add_u32 v219, v219, 4, v188
	v_xor_b32_e32 v188, 16, v219
	ds_read_b128 v[244:247], v219
	ds_read_b128 v[220:223], v188
	s_waitcnt vmcnt(9)
	s_waitcnt lgkmcnt(2)
	v_lshlrev_b32_e32 v184, 16, v148
	v_and_b32_e32 v185, 0xffff0000, v148
	v_lshlrev_b32_e32 v186, 16, v180
	v_and_b32_e32 v187, 0xffff0000, v180
	v_pk_fma_f32 v[234:235], v[234:235], v[184:185], v[186:187]
	v_lshlrev_b32_e32 v184, 16, v149
	v_and_b32_e32 v185, 0xffff0000, v149
	v_lshlrev_b32_e32 v186, 16, v181
	v_and_b32_e32 v187, 0xffff0000, v181
	v_pk_fma_f32 v[236:237], v[236:237], v[184:185], v[186:187]
	v_lshlrev_b32_e32 v184, 16, v150
	v_and_b32_e32 v185, 0xffff0000, v150
	v_lshlrev_b32_e32 v186, 16, v182
	v_and_b32_e32 v187, 0xffff0000, v182
	v_pk_fma_f32 v[228:229], v[228:229], v[184:185], v[186:187]
	v_lshlrev_b32_e32 v184, 16, v151
	v_and_b32_e32 v185, 0xffff0000, v151
	v_lshlrev_b32_e32 v186, 16, v183
	v_and_b32_e32 v187, 0xffff0000, v183
	v_pk_fma_f32 v[230:231], v[230:231], v[184:185], v[186:187]
	v_cvt_pk_bf16_f32 v148, v234, v235
	v_cvt_pk_bf16_f32 v149, v236, v237
	v_cvt_pk_bf16_f32 v150, v228, v229
	v_cvt_pk_bf16_f32 v151, v230, v231
	v_add_u32_e32 v219, 0x5000, v218
	global_store_dwordx4 v219, v[148:151], s[22:23]
	v_add_u32_e32 v219, 14, v212
	v_and_b32_e32 v219, 7, v219
	v_xor_b32_e32 v219, v213, v219
	v_add_u32_e32 v188, 14, v215
	v_lshlrev_b32_e32 v188, 10, v188
	v_lshl_add_u32 v219, v219, 4, v188
	v_xor_b32_e32 v188, 16, v219
	ds_read_b128 v[234:237], v219
	ds_read_b128 v[228:231], v188
	s_waitcnt vmcnt(8)
	s_waitcnt lgkmcnt(2)
	v_lshlrev_b32_e32 v184, 16, v152
	v_and_b32_e32 v185, 0xffff0000, v152
	v_lshlrev_b32_e32 v186, 16, v224
	v_and_b32_e32 v187, 0xffff0000, v224
	v_pk_fma_f32 v[244:245], v[244:245], v[184:185], v[186:187]
	v_lshlrev_b32_e32 v184, 16, v153
	v_and_b32_e32 v185, 0xffff0000, v153
	v_lshlrev_b32_e32 v186, 16, v225
	v_and_b32_e32 v187, 0xffff0000, v225
	v_pk_fma_f32 v[246:247], v[246:247], v[184:185], v[186:187]
	v_lshlrev_b32_e32 v184, 16, v154
	v_and_b32_e32 v185, 0xffff0000, v154
	v_lshlrev_b32_e32 v186, 16, v226
	v_and_b32_e32 v187, 0xffff0000, v226
	v_pk_fma_f32 v[220:221], v[220:221], v[184:185], v[186:187]
	v_lshlrev_b32_e32 v184, 16, v155
	v_and_b32_e32 v185, 0xffff0000, v155
	v_lshlrev_b32_e32 v186, 16, v227
	v_and_b32_e32 v187, 0xffff0000, v227
	v_pk_fma_f32 v[222:223], v[222:223], v[184:185], v[186:187]
	v_cvt_pk_bf16_f32 v152, v244, v245
	v_cvt_pk_bf16_f32 v153, v246, v247
	v_cvt_pk_bf16_f32 v154, v220, v221
	v_cvt_pk_bf16_f32 v155, v222, v223
	v_add_u32_e32 v219, 0x6000, v218
	global_store_dwordx4 v219, v[152:155], s[22:23]
	s_waitcnt vmcnt(7)
	s_waitcnt lgkmcnt(0)
	v_lshlrev_b32_e32 v184, 16, v156
	v_and_b32_e32 v185, 0xffff0000, v156
	v_lshlrev_b32_e32 v186, 16, v240
	v_and_b32_e32 v187, 0xffff0000, v240
	v_pk_fma_f32 v[234:235], v[234:235], v[184:185], v[186:187]
	v_lshlrev_b32_e32 v184, 16, v157
	v_and_b32_e32 v185, 0xffff0000, v157
	v_lshlrev_b32_e32 v186, 16, v241
	v_and_b32_e32 v187, 0xffff0000, v241
	v_pk_fma_f32 v[236:237], v[236:237], v[184:185], v[186:187]
	v_lshlrev_b32_e32 v184, 16, v158
	v_and_b32_e32 v185, 0xffff0000, v158
	v_lshlrev_b32_e32 v186, 16, v242
	v_and_b32_e32 v187, 0xffff0000, v242
	v_pk_fma_f32 v[228:229], v[228:229], v[184:185], v[186:187]
	v_lshlrev_b32_e32 v184, 16, v159
	v_and_b32_e32 v185, 0xffff0000, v159
	v_lshlrev_b32_e32 v186, 16, v243
	v_and_b32_e32 v187, 0xffff0000, v243
	v_pk_fma_f32 v[230:231], v[230:231], v[184:185], v[186:187]
	v_cvt_pk_bf16_f32 v156, v234, v235
	v_cvt_pk_bf16_f32 v157, v236, v237
	v_cvt_pk_bf16_f32 v158, v228, v229
	v_cvt_pk_bf16_f32 v159, v230, v231
	v_add_u32_e32 v219, 0x7000, v218
	global_store_dwordx4 v219, v[156:159], s[22:23]
	s_mov_b32 s61, 0xc000
	s_mov_b32 s60, 0x39800000
	s_mov_b64 s[8:9], 0x1000
	s_mov_b64 s[6:7], -1
	s_andn2_b64 vcc, exec, s[14:15]
	s_cbranch_vccnz .LBB0_1211
	s_andn2_b64 vcc, exec, s[16:17]
	s_cbranch_vccnz .LBB0_1210
	s_barrier
	s_branch .LBB0_1210

; #define EPI_FOR(u) \
;     _Pragma("unroll") for (int ai = 0; ai < 2; ++ai) _Pragma("unroll") for (int m = 0; m < 4; ++m) _Pragma("unroll") for (int bj = 0; bj < 2; ++bj)
; #define EPI_COL(u) (EPI_CB(u) + 8 * fq)
;     DI void operator()(const Acc& acc, const Unit& u, int wr, int wc, int fr, int fq) const {
;         EPI_FOR(u) {
;             const int row = EPI_ROW(u), col = EPI_COL(u); EPI_V(v);
;             const u32x4 gg = *(const u32x4*)(gate + (size_t)row * 3072 + gi * 1024 + col);
;             const float gf[8] = {bflo(gg.x), bfhi(gg.x), bflo(gg.y), bfhi(gg.y), bflo(gg.z), bfhi(gg.z), bflo(gg.w), bfhi(gg.w)};
;             bf16_t* mp = mrg + (size_t)row * 1024 + col;
;             if (accum) {
.LBB0_1248:
	s_lshl_b32 s2, s28, 8
	s_lshl_b32 s6, s29, 8
	v_readfirstlane_b32 s7, v232
	s_lshr_b32 s7, s7, 6
	s_lshl_b32 s7, s7, 4
	v_add_u32_e32 v210, s51, v145
	v_lshlrev_b32_e32 v210, 10, v210
	v_and_b32_e32 v211, 7, v145
	v_lshlrev_b32_e32 v212, 1, v144
	v_xor_b32_e32 v211, v212, v211
	v_lshl_add_u32 v210, v211, 4, v210
	s_lshl_b32 s8, s54, 2
	v_add_u32_e32 v210, s8, v210
	v_xor_b32_e32 v211, 16, v210
	v_lshrrev_b32_e32 v212, 5, v233
	v_and_b32_e32 v213, 31, v233
	v_lshl_add_u32 v214, v213, 3, s6
	v_lshlrev_b32_e32 v214, 1, v214
	v_lshlrev_b32_e32 v213, 1, v213

; #define EPI_FOR(u) \
;     _Pragma("unroll") for (int ai = 0; ai < 2; ++ai) _Pragma("unroll") for (int m = 0; m < 4; ++m) _Pragma("unroll") for (int bj = 0; bj < 2; ++bj)
; #define EPI_COL(u) (EPI_CB(u) + 8 * fq)
; DI u32x4 pack8(const float* v) { u32x4 w; w.x = pk2(v[0], v[1]); w.y = pk2(v[2], v[3]); w.z = pk2(v[4], v[5]); w.w = pk2(v[6], v[7]); return w; }
;     DI void operator()(const Acc& acc, const Unit& u, int wr, int wc, int fr, int fq) const {
;         EPI_FOR(u) {
;             const int row = EPI_ROW(u), col = EPI_COL(u); EPI_V(v);
;             const u32x4 gg = *(const u32x4*)(gate + (size_t)row * 3072 + gi * 1024 + col);
;             const float gf[8] = {bflo(gg.x), bfhi(gg.x), bflo(gg.y), bfhi(gg.y), bflo(gg.z), bfhi(gg.z), bflo(gg.w), bfhi(gg.w)};
;             bf16_t* mp = mrg + (size_t)row * 1024 + col;
;             if (accum) {
;                 const u32x4 oo = *(const u32x4*)mp;
;                 const float of[8] = {bflo(oo.x), bfhi(oo.x), bflo(oo.y), bfhi(oo.y), bflo(oo.z), bfhi(oo.z), bflo(oo.w), bfhi(oo.w)};
; #pragma unroll
;                 for (int j = 0; j < 8; ++j) v[j] = of[j] + gf[j] * v[j];
;             } else {
; #pragma unroll
;                 for (int j = 0; j < 8; ++j) v[j] = gf[j] * v[j];
;             }
;             *(u32x4*)mp = pack8(v);
;         }
	v_add_u32_e32 v215, s7, v212
	s_add_i32 s8, s2, 0
	v_add_u32_e32 v216, s8, v215
	v_mul_u32_u24_e32 v217, 0x1800, v216
	v_add_u32_e32 v217, v217, v214
	v_add_u32_e32 v217, 0x800, v217
	v_lshl_add_u32 v218, v216, 11, v214
	global_load_dwordx4 v[128:131], v217, s[22:23]
	global_load_dwordx4 v[160:163], v218, s[24:25]
	v_add_u32_e32 v219, 0x3000, v217
	global_load_dwordx4 v[132:135], v219, s[22:23]
	v_add_u32_e32 v219, 0x1000, v218
	global_load_dwordx4 v[164:167], v219, s[24:25]
	v_add_u32_e32 v219, 0x6000, v217
	global_load_dwordx4 v[136:139], v219, s[22:23]
	v_add_u32_e32 v219, 0x2000, v218
	global_load_dwordx4 v[168:171], v219, s[24:25]
	v_add_u32_e32 v219, 0x9000, v217
	global_load_dwordx4 v[140:143], v219, s[22:23]
	v_add_u32_e32 v219, 0x3000, v218
	global_load_dwordx4 v[172:175], v219, s[24:25]
	v_add_u32_e32 v219, 0xc000, v217
	global_load_dwordx4 v[144:147], v219, s[22:23]
	v_add_u32_e32 v219, 0x4000, v218
	global_load_dwordx4 v[176:179], v219, s[24:25]
	v_add_u32_e32 v219, 0xf000, v217
	global_load_dwordx4 v[148:151], v219, s[22:23]
	v_add_u32_e32 v219, 0x5000, v218
	global_load_dwordx4 v[180:183], v219, s[24:25]
	v_add_u32_e32 v219, 0x12000, v217
	global_load_dwordx4 v[152:155], v219, s[22:23]
	v_add_u32_e32 v219, 0x6000, v218
	global_load_dwordx4 v[224:227], v219, s[24:25]
	v_add_u32_e32 v219, 0x15000, v217
	global_load_dwordx4 v[156:159], v219, s[22:23]
	v_add_u32_e32 v219, 0x7000, v218
	global_load_dwordx4 v[240:243], v219, s[24:25]
	s_waitcnt vmcnt(16)
	s_barrier
	ds_write_b128 v210, v[124:127]
	ds_write_b128 v211, v[120:123]
	ds_write_b128 v210, v[116:119] offset:512
	ds_write_b128 v211, v[112:115] offset:512
	ds_write_b128 v210, v[108:111] offset:16384
	ds_write_b128 v211, v[104:107] offset:16384
	ds_write_b128 v210, v[100:103] offset:16896
	ds_write_b128 v211, v[96:99] offset:16896
	ds_write_b128 v210, v[92:95] offset:32768
	ds_write_b128 v211, v[88:91] offset:32768
	ds_write_b128 v210, v[84:87] offset:33280
	ds_write_b128 v211, v[80:83] offset:33280
	ds_write_b128 v210, v[76:79] offset:49152
	ds_write_b128 v211, v[72:75] offset:49152
	ds_write_b128 v210, v[68:71] offset:49664
	ds_write_b128 v211, v[64:67] offset:49664
	s_waitcnt lgkmcnt(0)
	s_barrier
	v_add_u32_e32 v219, 0, v212
	v_and_b32_e32 v219, 7, v219
	v_xor_b32_e32 v219, v213, v219
	v_add_u32_e32 v188, 0, v215
	v_lshlrev_b32_e32 v188, 10, v188
	v_lshl_add_u32 v219, v219, 4, v188
	v_xor_b32_e32 v188, 16, v219
	ds_read_b128 v[244:247], v219
	ds_read_b128 v[220:223], v188
	v_add_u32_e32 v219, 2, v212
	v_and_b32_e32 v219, 7, v219
	v_xor_b32_e32 v219, v213, v219
	v_add_u32_e32 v188, 2, v215
	v_lshlrev_b32_e32 v188, 10, v188
	v_lshl_add_u32 v219, v219, 4, v188
	v_xor_b32_e32 v188, 16, v219
	ds_read_b128 v[234:237], v219
	ds_read_b128 v[228:231], v188
	s_waitcnt vmcnt(14)
	s_waitcnt lgkmcnt(2)
	v_lshlrev_b32_e32 v184, 16, v128
	v_and_b32_e32 v185, 0xffff0000, v128
	v_lshlrev_b32_e32 v186, 16, v160
	v_and_b32_e32 v187, 0xffff0000, v160
	v_pk_fma_f32 v[244:245], v[244:245], v[184:185], v[186:187]
	v_lshlrev_b32_e32 v184, 16, v129
	v_and_b32_e32 v185, 0xffff0000, v129
	v_lshlrev_b32_e32 v186, 16, v161
	v_and_b32_e32 v187, 0xffff0000, v161
	v_pk_fma_f32 v[246:247], v[246:247], v[184:185], v[186:187]
	v_lshlrev_b32_e32 v184, 16, v130
	v_and_b32_e32 v185, 0xffff0000, v130
	v_lshlrev_b32_e32 v186, 16, v162
	v_and_b32_e32 v187, 0xffff0000, v162
	v_pk_fma_f32 v[220:221], v[220:221], v[184:185], v[186:187]
	v_lshlrev_b32_e32 v184, 16, v131
	v_and_b32_e32 v185, 0xffff0000, v131
	v_lshlrev_b32_e32 v186, 16, v163
	v_and_b32_e32 v187, 0xffff0000, v163
	v_pk_fma_f32 v[222:223], v[222:223], v[184:185], v[186:187]
	v_cvt_pk_bf16_f32 v128, v244, v245
	v_cvt_pk_bf16_f32 v129, v246, v247
	v_cvt_pk_bf16_f32 v130, v220, v221
	v_cvt_pk_bf16_f32 v131, v222, v223
	global_store_dwordx4 v218, v[128:131], s[24:25]
	v_add_u32_e32 v219, 4, v212
	v_and_b32_e32 v219, 7, v219
	v_xor_b32_e32 v219, v213, v219
	v_add_u32_e32 v188, 4, v215
	v_lshlrev_b32_e32 v188, 10, v188
	v_lshl_add_u32 v219, v219, 4, v188
	v_xor_b32_e32 v188, 16, v219
	ds_read_b128 v[244:247], v219
	ds_read_b128 v[220:223], v188
	s_waitcnt vmcnt(13)
	s_waitcnt lgkmcnt(2)
	v_lshlrev_b32_e32 v184, 16, v132
	v_and_b32_e32 v185, 0xffff0000, v132
	v_lshlrev_b32_e32 v186, 16, v164
	v_and_b32_e32 v187, 0xffff0000, v164
	v_pk_fma_f32 v[234:235], v[234:235], v[184:185], v[186:187]
	v_lshlrev_b32_e32 v184, 16, v133
	v_and_b32_e32 v185, 0xffff0000, v133
	v_lshlrev_b32_e32 v186, 16, v165
	v_and_b32_e32 v187, 0xffff0000, v165
	v_pk_fma_f32 v[236:237], v[236:237], v[184:185], v[186:187]
	v_lshlrev_b32_e32 v184, 16, v134
	v_and_b32_e32 v185, 0xffff0000, v134
	v_lshlrev_b32_e32 v186, 16, v166
	v_and_b32_e32 v187, 0xffff0000, v166
	v_pk_fma_f32 v[228:229], v[228:229], v[184:185], v[186:187]
	v_lshlrev_b32_e32 v184, 16, v135
	v_and_b32_e32 v185, 0xffff0000, v135
	v_lshlrev_b32_e32 v186, 16, v167
	v_and_b32_e32 v187, 0xffff0000, v167
	v_pk_fma_f32 v[230:231], v[230:231], v[184:185], v[186:187]
	v_cvt_pk_bf16_f32 v132, v234, v235
	v_cvt_pk_bf16_f32 v133, v236, v237
	v_cvt_pk_bf16_f32 v134, v228, v229
	v_cvt_pk_bf16_f32 v135, v230, v231
	v_add_u32_e32 v219, 0x1000, v218
	global_store_dwordx4 v219, v[132:135], s[24:25]
	v_add_u32_e32 v219, 6, v212
	v_and_b32_e32 v219, 7, v219
	v_xor_b32_e32 v219, v213, v219
	v_add_u32_e32 v188, 6, v215
	v_lshlrev_b32_e32 v188, 10, v188
	v_lshl_add_u32 v219, v219, 4, v188
	v_xor_b32_e32 v188, 16, v219
	ds_read_b128 v[234:237], v219
	ds_read_b128 v[228:231], v188
	s_waitcnt vmcnt(12)
	s_waitcnt lgkmcnt(2)
; #define EPI_FOR(u) \
;     _Pragma("unroll") for (int ai = 0; ai < 2; ++ai) _Pragma("unroll") for (int m = 0; m < 4; ++m) _Pragma("unroll") for (int bj = 0; bj < 2; ++bj)
; #define EPI_COL(u) (EPI_CB(u) + 8 * fq)
; DI u32x4 pack8(const float* v) { u32x4 w; w.x = pk2(v[0], v[1]); w.y = pk2(v[2], v[3]); w.z = pk2(v[4], v[5]); w.w = pk2(v[6], v[7]); return w; }
;     DI void operator()(const Acc& acc, const Unit& u, int wr, int wc, int fr, int fq) const {
;         EPI_FOR(u) {
;             const int row = EPI_ROW(u), col = EPI_COL(u); EPI_V(v);
;             const u32x4 gg = *(const u32x4*)(gate + (size_t)row * 3072 + gi * 1024 + col);
;             const float gf[8] = {bflo(gg.x), bfhi(gg.x), bflo(gg.y), bfhi(gg.y), bflo(gg.z), bfhi(gg.z), bflo(gg.w), bfhi(gg.w)};
;             bf16_t* mp = mrg + (size_t)row * 1024 + col;
;             if (accum) {
;                 const u32x4 oo = *(const u32x4*)mp;
;                 const float of[8] = {bflo(oo.x), bfhi(oo.x), bflo(oo.y), bfhi(oo.y), bflo(oo.z), bfhi(oo.z), bflo(oo.w), bfhi(oo.w)};
; #pragma unroll
;                 for (int j = 0; j < 8; ++j) v[j] = of[j] + gf[j] * v[j];
;             } else {
; #pragma unroll
;                 for (int j = 0; j < 8; ++j) v[j] = gf[j] * v[j];
;             }
;             *(u32x4*)mp = pack8(v);
;         }
	v_lshlrev_b32_e32 v184, 16, v136
	v_and_b32_e32 v185, 0xffff0000, v136
	v_lshlrev_b32_e32 v186, 16, v168
	v_and_b32_e32 v187, 0xffff0000, v168
	v_pk_fma_f32 v[244:245], v[244:245], v[184:185], v[186:187]
	v_lshlrev_b32_e32 v184, 16, v137
	v_and_b32_e32 v185, 0xffff0000, v137
	v_lshlrev_b32_e32 v186, 16, v169
	v_and_b32_e32 v187, 0xffff0000, v169
	v_pk_fma_f32 v[246:247], v[246:247], v[184:185], v[186:187]
	v_lshlrev_b32_e32 v184, 16, v138
	v_and_b32_e32 v185, 0xffff0000, v138
	v_lshlrev_b32_e32 v186, 16, v170
	v_and_b32_e32 v187, 0xffff0000, v170
	v_pk_fma_f32 v[220:221], v[220:221], v[184:185], v[186:187]
	v_lshlrev_b32_e32 v184, 16, v139
	v_and_b32_e32 v185, 0xffff0000, v139
	v_lshlrev_b32_e32 v186, 16, v171
	v_and_b32_e32 v187, 0xffff0000, v171
	v_pk_fma_f32 v[222:223], v[222:223], v[184:185], v[186:187]
	v_cvt_pk_bf16_f32 v136, v244, v245
	v_cvt_pk_bf16_f32 v137, v246, v247
	v_cvt_pk_bf16_f32 v138, v220, v221
	v_cvt_pk_bf16_f32 v139, v222, v223
	v_add_u32_e32 v219, 0x2000, v218
	global_store_dwordx4 v219, v[136:139], s[24:25]
	v_add_u32_e32 v219, 8, v212
	v_and_b32_e32 v219, 7, v219
	v_xor_b32_e32 v219, v213, v219
	v_add_u32_e32 v188, 8, v215
	v_lshlrev_b32_e32 v188, 10, v188
	v_lshl_add_u32 v219, v219, 4, v188
	v_xor_b32_e32 v188, 16, v219
	ds_read_b128 v[244:247], v219
	ds_read_b128 v[220:223], v188
	s_waitcnt vmcnt(11)
	s_waitcnt lgkmcnt(2)
	v_lshlrev_b32_e32 v184, 16, v140
	v_and_b32_e32 v185, 0xffff0000, v140
	v_lshlrev_b32_e32 v186, 16, v172
	v_and_b32_e32 v187, 0xffff0000, v172
	v_pk_fma_f32 v[234:235], v[234:235], v[184:185], v[186:187]
	v_lshlrev_b32_e32 v184, 16, v141
	v_and_b32_e32 v185, 0xffff0000, v141
	v_lshlrev_b32_e32 v186, 16, v173
	v_and_b32_e32 v187, 0xffff0000, v173
	v_pk_fma_f32 v[236:237], v[236:237], v[184:185], v[186:187]
	v_lshlrev_b32_e32 v184, 16, v142
	v_and_b32_e32 v185, 0xffff0000, v142
	v_lshlrev_b32_e32 v186, 16, v174
	v_and_b32_e32 v187, 0xffff0000, v174
	v_pk_fma_f32 v[228:229], v[228:229], v[184:185], v[186:187]
	v_lshlrev_b32_e32 v184, 16, v143
	v_and_b32_e32 v185, 0xffff0000, v143
	v_lshlrev_b32_e32 v186, 16, v175
	v_and_b32_e32 v187, 0xffff0000, v175
	v_pk_fma_f32 v[230:231], v[230:231], v[184:185], v[186:187]
	v_cvt_pk_bf16_f32 v140, v234, v235
	v_cvt_pk_bf16_f32 v141, v236, v237
	v_cvt_pk_bf16_f32 v142, v228, v229
	v_cvt_pk_bf16_f32 v143, v230, v231
	v_add_u32_e32 v219, 0x3000, v218
	global_store_dwordx4 v219, v[140:143], s[24:25]
	v_add_u32_e32 v219, 10, v212
	v_and_b32_e32 v219, 7, v219
	v_xor_b32_e32 v219, v213, v219
	v_add_u32_e32 v188, 10, v215
	v_lshlrev_b32_e32 v188, 10, v188
	v_lshl_add_u32 v219, v219, 4, v188
	v_xor_b32_e32 v188, 16, v219
	ds_read_b128 v[234:237], v219
	ds_read_b128 v[228:231], v188
	s_waitcnt vmcnt(10)
	s_waitcnt lgkmcnt(2)
	v_lshlrev_b32_e32 v184, 16, v144
	v_and_b32_e32 v185, 0xffff0000, v144
	v_lshlrev_b32_e32 v186, 16, v176
	v_and_b32_e32 v187, 0xffff0000, v176
	v_pk_fma_f32 v[244:245], v[244:245], v[184:185], v[186:187]
	v_lshlrev_b32_e32 v184, 16, v145
	v_and_b32_e32 v185, 0xffff0000, v145
	v_lshlrev_b32_e32 v186, 16, v177
	v_and_b32_e32 v187, 0xffff0000, v177
	v_pk_fma_f32 v[246:247], v[246:247], v[184:185], v[186:187]
	v_lshlrev_b32_e32 v184, 16, v146
	v_and_b32_e32 v185, 0xffff0000, v146
	v_lshlrev_b32_e32 v186, 16, v178
	v_and_b32_e32 v187, 0xffff0000, v178
	v_pk_fma_f32 v[220:221], v[220:221], v[184:185], v[186:187]
	v_lshlrev_b32_e32 v184, 16, v147
	v_and_b32_e32 v185, 0xffff0000, v147
	v_lshlrev_b32_e32 v186, 16, v179
	v_and_b32_e32 v187, 0xffff0000, v179
	v_pk_fma_f32 v[222:223], v[222:223], v[184:185], v[186:187]
	v_cvt_pk_bf16_f32 v144, v244, v245
	v_cvt_pk_bf16_f32 v145, v246, v247
	v_cvt_pk_bf16_f32 v146, v220, v221
	v_cvt_pk_bf16_f32 v147, v222, v223
	v_add_u32_e32 v219, 0x4000, v218
	global_store_dwordx4 v219, v[144:147], s[24:25]
	v_add_u32_e32 v219, 12, v212
	v_and_b32_e32 v219, 7, v219
	v_xor_b32_e32 v219, v213, v219
	v_add_u32_e32 v188, 12, v215
	v_lshlrev_b32_e32 v188, 10, v188
	v_lshl_add_u32 v219, v219, 4, v188
	v_xor_b32_e32 v188, 16, v219
	ds_read_b128 v[244:247], v219
	ds_read_b128 v[220:223], v188
	s_waitcnt vmcnt(9)
	s_waitcnt lgkmcnt(2)
	v_lshlrev_b32_e32 v184, 16, v148
	v_and_b32_e32 v185, 0xffff0000, v148
	v_lshlrev_b32_e32 v186, 16, v180
	v_and_b32_e32 v187, 0xffff0000, v180
	v_pk_fma_f32 v[234:235], v[234:235], v[184:185], v[186:187]
	v_lshlrev_b32_e32 v184, 16, v149
	v_and_b32_e32 v185, 0xffff0000, v149
	v_lshlrev_b32_e32 v186, 16, v181
	v_and_b32_e32 v187, 0xffff0000, v181
	v_pk_fma_f32 v[236:237], v[236:237], v[184:185], v[186:187]
	v_lshlrev_b32_e32 v184, 16, v150
	v_and_b32_e32 v185, 0xffff0000, v150
	v_lshlrev_b32_e32 v186, 16, v182
	v_and_b32_e32 v187, 0xffff0000, v182
	v_pk_fma_f32 v[228:229], v[228:229], v[184:185], v[186:187]
	v_lshlrev_b32_e32 v184, 16, v151
	v_and_b32_e32 v185, 0xffff0000, v151
	v_lshlrev_b32_e32 v186, 16, v183
	v_and_b32_e32 v187, 0xffff0000, v183
	v_pk_fma_f32 v[230:231], v[230:231], v[184:185], v[186:187]
	v_cvt_pk_bf16_f32 v148, v234, v235
	v_cvt_pk_bf16_f32 v149, v236, v237
	v_cvt_pk_bf16_f32 v150, v228, v229
	v_cvt_pk_bf16_f32 v151, v230, v231
	v_add_u32_e32 v219, 0x5000, v218
	global_store_dwordx4 v219, v[148:151], s[24:25]
	v_add_u32_e32 v219, 14, v212
	v_and_b32_e32 v219, 7, v219
	v_xor_b32_e32 v219, v213, v219
	v_add_u32_e32 v188, 14, v215
	v_lshlrev_b32_e32 v188, 10, v188
	v_lshl_add_u32 v219, v219, 4, v188
	v_xor_b32_e32 v188, 16, v219
	ds_read_b128 v[234:237], v219
	ds_read_b128 v[228:231], v188
	s_waitcnt vmcnt(8)
	s_waitcnt lgkmcnt(2)
; #define EPI_FOR(u) \
;     _Pragma("unroll") for (int ai = 0; ai < 2; ++ai) _Pragma("unroll") for (int m = 0; m < 4; ++m) _Pragma("unroll") for (int bj = 0; bj < 2; ++bj)
; #define EPI_COL(u) (EPI_CB(u) + 8 * fq)
; DI u32x4 pack8(const float* v) { u32x4 w; w.x = pk2(v[0], v[1]); w.y = pk2(v[2], v[3]); w.z = pk2(v[4], v[5]); w.w = pk2(v[6], v[7]); return w; }
;     DI void operator()(const Acc& acc, const Unit& u, int wr, int wc, int fr, int fq) const {
;         EPI_FOR(u) {
;             const int row = EPI_ROW(u), col = EPI_COL(u); EPI_V(v);
;             const u32x4 gg = *(const u32x4*)(gate + (size_t)row * 3072 + gi * 1024 + col);
;             const float gf[8] = {bflo(gg.x), bfhi(gg.x), bflo(gg.y), bfhi(gg.y), bflo(gg.z), bfhi(gg.z), bflo(gg.w), bfhi(gg.w)};
;             bf16_t* mp = mrg + (size_t)row * 1024 + col;
;             if (accum) {
;                 const u32x4 oo = *(const u32x4*)mp;
;                 const float of[8] = {bflo(oo.x), bfhi(oo.x), bflo(oo.y), bfhi(oo.y), bflo(oo.z), bfhi(oo.z), bflo(oo.w), bfhi(oo.w)};
; #pragma unroll
;                 for (int j = 0; j < 8; ++j) v[j] = of[j] + gf[j] * v[j];
;             } else {
; #pragma unroll
;                 for (int j = 0; j < 8; ++j) v[j] = gf[j] * v[j];
;             }
;             *(u32x4*)mp = pack8(v);
;         }
	v_lshlrev_b32_e32 v184, 16, v152
	v_and_b32_e32 v185, 0xffff0000, v152
	v_lshlrev_b32_e32 v186, 16, v224
	v_and_b32_e32 v187, 0xffff0000, v224
	v_pk_fma_f32 v[244:245], v[244:245], v[184:185], v[186:187]
	v_lshlrev_b32_e32 v184, 16, v153
	v_and_b32_e32 v185, 0xffff0000, v153
	v_lshlrev_b32_e32 v186, 16, v225
	v_and_b32_e32 v187, 0xffff0000, v225
	v_pk_fma_f32 v[246:247], v[246:247], v[184:185], v[186:187]
	v_lshlrev_b32_e32 v184, 16, v154
	v_and_b32_e32 v185, 0xffff0000, v154
	v_lshlrev_b32_e32 v186, 16, v226
	v_and_b32_e32 v187, 0xffff0000, v226
	v_pk_fma_f32 v[220:221], v[220:221], v[184:185], v[186:187]
	v_lshlrev_b32_e32 v184, 16, v155
	v_and_b32_e32 v185, 0xffff0000, v155
	v_lshlrev_b32_e32 v186, 16, v227
	v_and_b32_e32 v187, 0xffff0000, v227
	v_pk_fma_f32 v[222:223], v[222:223], v[184:185], v[186:187]
	v_cvt_pk_bf16_f32 v152, v244, v245
	v_cvt_pk_bf16_f32 v153, v246, v247
	v_cvt_pk_bf16_f32 v154, v220, v221
	v_cvt_pk_bf16_f32 v155, v222, v223
	v_add_u32_e32 v219, 0x6000, v218
	global_store_dwordx4 v219, v[152:155], s[24:25]
	s_waitcnt vmcnt(7)
	s_waitcnt lgkmcnt(0)
	v_lshlrev_b32_e32 v184, 16, v156
	v_and_b32_e32 v185, 0xffff0000, v156
	v_lshlrev_b32_e32 v186, 16, v240
	v_and_b32_e32 v187, 0xffff0000, v240
	v_pk_fma_f32 v[234:235], v[234:235], v[184:185], v[186:187]
	v_lshlrev_b32_e32 v184, 16, v157
	v_and_b32_e32 v185, 0xffff0000, v157
	v_lshlrev_b32_e32 v186, 16, v241
	v_and_b32_e32 v187, 0xffff0000, v241
	v_pk_fma_f32 v[236:237], v[236:237], v[184:185], v[186:187]
	v_lshlrev_b32_e32 v184, 16, v158
	v_and_b32_e32 v185, 0xffff0000, v158
	v_lshlrev_b32_e32 v186, 16, v242
	v_and_b32_e32 v187, 0xffff0000, v242
	v_pk_fma_f32 v[228:229], v[228:229], v[184:185], v[186:187]
	v_lshlrev_b32_e32 v184, 16, v159
	v_and_b32_e32 v185, 0xffff0000, v159
	v_lshlrev_b32_e32 v186, 16, v243
	v_and_b32_e32 v187, 0xffff0000, v243
	v_pk_fma_f32 v[230:231], v[230:231], v[184:185], v[186:187]
	v_cvt_pk_bf16_f32 v156, v234, v235
	v_cvt_pk_bf16_f32 v157, v236, v237
	v_cvt_pk_bf16_f32 v158, v228, v229
	v_cvt_pk_bf16_f32 v159, v230, v231
	v_add_u32_e32 v219, 0x7000, v218
	global_store_dwordx4 v219, v[156:159], s[24:25]
	v_add_u32_e32 v215, s7, v212
	s_add_i32 s8, s2, 128
	v_add_u32_e32 v216, s8, v215
	v_mul_u32_u24_e32 v217, 0x1800, v216
	v_add_u32_e32 v217, v217, v214
	v_add_u32_e32 v217, 0x800, v217
	v_lshl_add_u32 v218, v216, 11, v214
	global_load_dwordx4 v[128:131], v217, s[22:23]
	global_load_dwordx4 v[160:163], v218, s[24:25]
	v_add_u32_e32 v219, 0x3000, v217
	global_load_dwordx4 v[132:135], v219, s[22:23]
	v_add_u32_e32 v219, 0x1000, v218
	global_load_dwordx4 v[164:167], v219, s[24:25]
	v_add_u32_e32 v219, 0x6000, v217
	global_load_dwordx4 v[136:139], v219, s[22:23]
	v_add_u32_e32 v219, 0x2000, v218
	global_load_dwordx4 v[168:171], v219, s[24:25]
	v_add_u32_e32 v219, 0x9000, v217
	global_load_dwordx4 v[140:143], v219, s[22:23]
	v_add_u32_e32 v219, 0x3000, v218
	global_load_dwordx4 v[172:175], v219, s[24:25]
	v_add_u32_e32 v219, 0xc000, v217
	global_load_dwordx4 v[144:147], v219, s[22:23]
	v_add_u32_e32 v219, 0x4000, v218
	global_load_dwordx4 v[176:179], v219, s[24:25]
	v_add_u32_e32 v219, 0xf000, v217
	global_load_dwordx4 v[148:151], v219, s[22:23]
	v_add_u32_e32 v219, 0x5000, v218
	global_load_dwordx4 v[180:183], v219, s[24:25]
	v_add_u32_e32 v219, 0x12000, v217
	global_load_dwordx4 v[152:155], v219, s[22:23]
	v_add_u32_e32 v219, 0x6000, v218
	global_load_dwordx4 v[224:227], v219, s[24:25]
	v_add_u32_e32 v219, 0x15000, v217
	global_load_dwordx4 v[156:159], v219, s[22:23]
	v_add_u32_e32 v219, 0x7000, v218
	global_load_dwordx4 v[240:243], v219, s[24:25]
	s_barrier
	ds_write_b128 v210, v[60:63]
	ds_write_b128 v211, v[56:59]
	ds_write_b128 v210, v[52:55] offset:512
	ds_write_b128 v211, v[48:51] offset:512
	ds_write_b128 v210, v[44:47] offset:16384
	ds_write_b128 v211, v[40:43] offset:16384
	ds_write_b128 v210, v[36:39] offset:16896
	ds_write_b128 v211, v[32:35] offset:16896
	ds_write_b128 v210, v[28:31] offset:32768
	ds_write_b128 v211, v[24:27] offset:32768
	ds_write_b128 v210, v[20:23] offset:33280
	ds_write_b128 v211, v[16:19] offset:33280
	ds_write_b128 v210, v[12:15] offset:49152
	ds_write_b128 v211, v[8:11] offset:49152
	ds_write_b128 v210, v[4:7] offset:49664
	ds_write_b128 v211, v[0:3] offset:49664
	s_waitcnt lgkmcnt(0)
	s_barrier
; #define EPI_FOR(u) \
;     _Pragma("unroll") for (int ai = 0; ai < 2; ++ai) _Pragma("unroll") for (int m = 0; m < 4; ++m) _Pragma("unroll") for (int bj = 0; bj < 2; ++bj)
; #define EPI_COL(u) (EPI_CB(u) + 8 * fq)
; DI u32x4 pack8(const float* v) { u32x4 w; w.x = pk2(v[0], v[1]); w.y = pk2(v[2], v[3]); w.z = pk2(v[4], v[5]); w.w = pk2(v[6], v[7]); return w; }
;     DI void operator()(const Acc& acc, const Unit& u, int wr, int wc, int fr, int fq) const {
;         EPI_FOR(u) {
;             const int row = EPI_ROW(u), col = EPI_COL(u); EPI_V(v);
;             const u32x4 gg = *(const u32x4*)(gate + (size_t)row * 3072 + gi * 1024 + col);
;             const float gf[8] = {bflo(gg.x), bfhi(gg.x), bflo(gg.y), bfhi(gg.y), bflo(gg.z), bfhi(gg.z), bflo(gg.w), bfhi(gg.w)};
;             bf16_t* mp = mrg + (size_t)row * 1024 + col;
;             if (accum) {
;                 const u32x4 oo = *(const u32x4*)mp;
;                 const float of[8] = {bflo(oo.x), bfhi(oo.x), bflo(oo.y), bfhi(oo.y), bflo(oo.z), bfhi(oo.z), bflo(oo.w), bfhi(oo.w)};
; #pragma unroll
;                 for (int j = 0; j < 8; ++j) v[j] = of[j] + gf[j] * v[j];
;             } else {
; #pragma unroll
;                 for (int j = 0; j < 8; ++j) v[j] = gf[j] * v[j];
;             }
;             *(u32x4*)mp = pack8(v);
;         }
	v_add_u32_e32 v219, 0, v212
	v_and_b32_e32 v219, 7, v219
	v_xor_b32_e32 v219, v213, v219
	v_add_u32_e32 v188, 0, v215
	v_lshlrev_b32_e32 v188, 10, v188
	v_lshl_add_u32 v219, v219, 4, v188
	v_xor_b32_e32 v188, 16, v219
	ds_read_b128 v[244:247], v219
	ds_read_b128 v[220:223], v188
	v_add_u32_e32 v219, 2, v212
	v_and_b32_e32 v219, 7, v219
	v_xor_b32_e32 v219, v213, v219
	v_add_u32_e32 v188, 2, v215
	v_lshlrev_b32_e32 v188, 10, v188
	v_lshl_add_u32 v219, v219, 4, v188
	v_xor_b32_e32 v188, 16, v219
	ds_read_b128 v[234:237], v219
	ds_read_b128 v[228:231], v188
	s_waitcnt vmcnt(14)
	s_waitcnt lgkmcnt(2)
	v_lshlrev_b32_e32 v184, 16, v128
	v_and_b32_e32 v185, 0xffff0000, v128
	v_lshlrev_b32_e32 v186, 16, v160
	v_and_b32_e32 v187, 0xffff0000, v160
	v_pk_fma_f32 v[244:245], v[244:245], v[184:185], v[186:187]
	v_lshlrev_b32_e32 v184, 16, v129
	v_and_b32_e32 v185, 0xffff0000, v129
	v_lshlrev_b32_e32 v186, 16, v161
	v_and_b32_e32 v187, 0xffff0000, v161
	v_pk_fma_f32 v[246:247], v[246:247], v[184:185], v[186:187]
	v_lshlrev_b32_e32 v184, 16, v130
	v_and_b32_e32 v185, 0xffff0000, v130
	v_lshlrev_b32_e32 v186, 16, v162
	v_and_b32_e32 v187, 0xffff0000, v162
	v_pk_fma_f32 v[220:221], v[220:221], v[184:185], v[186:187]
	v_lshlrev_b32_e32 v184, 16, v131
	v_and_b32_e32 v185, 0xffff0000, v131
	v_lshlrev_b32_e32 v186, 16, v163
	v_and_b32_e32 v187, 0xffff0000, v163
	v_pk_fma_f32 v[222:223], v[222:223], v[184:185], v[186:187]
	v_cvt_pk_bf16_f32 v128, v244, v245
	v_cvt_pk_bf16_f32 v129, v246, v247
	v_cvt_pk_bf16_f32 v130, v220, v221
	v_cvt_pk_bf16_f32 v131, v222, v223
	global_store_dwordx4 v218, v[128:131], s[24:25]
	v_add_u32_e32 v219, 4, v212
	v_and_b32_e32 v219, 7, v219
	v_xor_b32_e32 v219, v213, v219
	v_add_u32_e32 v188, 4, v215
	v_lshlrev_b32_e32 v188, 10, v188
	v_lshl_add_u32 v219, v219, 4, v188
	v_xor_b32_e32 v188, 16, v219
	ds_read_b128 v[244:247], v219
	ds_read_b128 v[220:223], v188
	s_waitcnt vmcnt(13)
	s_waitcnt lgkmcnt(2)
	v_lshlrev_b32_e32 v184, 16, v132
	v_and_b32_e32 v185, 0xffff0000, v132
	v_lshlrev_b32_e32 v186, 16, v164
	v_and_b32_e32 v187, 0xffff0000, v164
	v_pk_fma_f32 v[234:235], v[234:235], v[184:185], v[186:187]
	v_lshlrev_b32_e32 v184, 16, v133
	v_and_b32_e32 v185, 0xffff0000, v133
	v_lshlrev_b32_e32 v186, 16, v165
	v_and_b32_e32 v187, 0xffff0000, v165
	v_pk_fma_f32 v[236:237], v[236:237], v[184:185], v[186:187]
	v_lshlrev_b32_e32 v184, 16, v134
	v_and_b32_e32 v185, 0xffff0000, v134
	v_lshlrev_b32_e32 v186, 16, v166
	v_and_b32_e32 v187, 0xffff0000, v166
	v_pk_fma_f32 v[228:229], v[228:229], v[184:185], v[186:187]
	v_lshlrev_b32_e32 v184, 16, v135
	v_and_b32_e32 v185, 0xffff0000, v135
	v_lshlrev_b32_e32 v186, 16, v167
	v_and_b32_e32 v187, 0xffff0000, v167
	v_pk_fma_f32 v[230:231], v[230:231], v[184:185], v[186:187]
	v_cvt_pk_bf16_f32 v132, v234, v235
	v_cvt_pk_bf16_f32 v133, v236, v237
	v_cvt_pk_bf16_f32 v134, v228, v229
	v_cvt_pk_bf16_f32 v135, v230, v231
	v_add_u32_e32 v219, 0x1000, v218
	global_store_dwordx4 v219, v[132:135], s[24:25]
	v_add_u32_e32 v219, 6, v212
	v_and_b32_e32 v219, 7, v219
	v_xor_b32_e32 v219, v213, v219
	v_add_u32_e32 v188, 6, v215
	v_lshlrev_b32_e32 v188, 10, v188
	v_lshl_add_u32 v219, v219, 4, v188
	v_xor_b32_e32 v188, 16, v219
	ds_read_b128 v[234:237], v219
	ds_read_b128 v[228:231], v188
	s_waitcnt vmcnt(12)
	s_waitcnt lgkmcnt(2)
	v_lshlrev_b32_e32 v184, 16, v136
	v_and_b32_e32 v185, 0xffff0000, v136
	v_lshlrev_b32_e32 v186, 16, v168
	v_and_b32_e32 v187, 0xffff0000, v168
	v_pk_fma_f32 v[244:245], v[244:245], v[184:185], v[186:187]
	v_lshlrev_b32_e32 v184, 16, v137
	v_and_b32_e32 v185, 0xffff0000, v137
	v_lshlrev_b32_e32 v186, 16, v169
	v_and_b32_e32 v187, 0xffff0000, v169
	v_pk_fma_f32 v[246:247], v[246:247], v[184:185], v[186:187]
	v_lshlrev_b32_e32 v184, 16, v138
	v_and_b32_e32 v185, 0xffff0000, v138
	v_lshlrev_b32_e32 v186, 16, v170
	v_and_b32_e32 v187, 0xffff0000, v170
	v_pk_fma_f32 v[220:221], v[220:221], v[184:185], v[186:187]
	v_lshlrev_b32_e32 v184, 16, v139
	v_and_b32_e32 v185, 0xffff0000, v139
	v_lshlrev_b32_e32 v186, 16, v171
	v_and_b32_e32 v187, 0xffff0000, v171
	v_pk_fma_f32 v[222:223], v[222:223], v[184:185], v[186:187]
	v_cvt_pk_bf16_f32 v136, v244, v245
	v_cvt_pk_bf16_f32 v137, v246, v247
	v_cvt_pk_bf16_f32 v138, v220, v221
	v_cvt_pk_bf16_f32 v139, v222, v223
	v_add_u32_e32 v219, 0x2000, v218
	global_store_dwordx4 v219, v[136:139], s[24:25]
	v_add_u32_e32 v219, 8, v212
	v_and_b32_e32 v219, 7, v219
	v_xor_b32_e32 v219, v213, v219
	v_add_u32_e32 v188, 8, v215
	v_lshlrev_b32_e32 v188, 10, v188
	v_lshl_add_u32 v219, v219, 4, v188
	v_xor_b32_e32 v188, 16, v219
	ds_read_b128 v[244:247], v219
	ds_read_b128 v[220:223], v188
	s_waitcnt vmcnt(11)
	s_waitcnt lgkmcnt(2)
	v_lshlrev_b32_e32 v184, 16, v140
	v_and_b32_e32 v185, 0xffff0000, v140
	v_lshlrev_b32_e32 v186, 16, v172
	v_and_b32_e32 v187, 0xffff0000, v172
	v_pk_fma_f32 v[234:235], v[234:235], v[184:185], v[186:187]
	v_lshlrev_b32_e32 v184, 16, v141
	v_and_b32_e32 v185, 0xffff0000, v141
	v_lshlrev_b32_e32 v186, 16, v173
	v_and_b32_e32 v187, 0xffff0000, v173
	v_pk_fma_f32 v[236:237], v[236:237], v[184:185], v[186:187]
	v_lshlrev_b32_e32 v184, 16, v142
	v_and_b32_e32 v185, 0xffff0000, v142
	v_lshlrev_b32_e32 v186, 16, v174
	v_and_b32_e32 v187, 0xffff0000, v174
	v_pk_fma_f32 v[228:229], v[228:229], v[184:185], v[186:187]
	v_lshlrev_b32_e32 v184, 16, v143
	v_and_b32_e32 v185, 0xffff0000, v143
	v_lshlrev_b32_e32 v186, 16, v175
	v_and_b32_e32 v187, 0xffff0000, v175
	v_pk_fma_f32 v[230:231], v[230:231], v[184:185], v[186:187]
	v_cvt_pk_bf16_f32 v140, v234, v235
	v_cvt_pk_bf16_f32 v141, v236, v237
	v_cvt_pk_bf16_f32 v142, v228, v229
	v_cvt_pk_bf16_f32 v143, v230, v231
	v_add_u32_e32 v219, 0x3000, v218
	global_store_dwordx4 v219, v[140:143], s[24:25]
	v_add_u32_e32 v219, 10, v212
	v_and_b32_e32 v219, 7, v219
	v_xor_b32_e32 v219, v213, v219
	v_add_u32_e32 v188, 10, v215
	v_lshlrev_b32_e32 v188, 10, v188
	v_lshl_add_u32 v219, v219, 4, v188
	v_xor_b32_e32 v188, 16, v219
	ds_read_b128 v[234:237], v219
	ds_read_b128 v[228:231], v188
	s_waitcnt vmcnt(10)
; #define EPI_FOR(u) \
;     _Pragma("unroll") for (int ai = 0; ai < 2; ++ai) _Pragma("unroll") for (int m = 0; m < 4; ++m) _Pragma("unroll") for (int bj = 0; bj < 2; ++bj)
; #define EPI_COL(u) (EPI_CB(u) + 8 * fq)
; DI u32x4 pack8(const float* v) { u32x4 w; w.x = pk2(v[0], v[1]); w.y = pk2(v[2], v[3]); w.z = pk2(v[4], v[5]); w.w = pk2(v[6], v[7]); return w; }
;     DI void operator()(const Acc& acc, const Unit& u, int wr, int wc, int fr, int fq) const {
;         EPI_FOR(u) {
;             const int row = EPI_ROW(u), col = EPI_COL(u); EPI_V(v);
;             const u32x4 gg = *(const u32x4*)(gate + (size_t)row * 3072 + gi * 1024 + col);
;             const float gf[8] = {bflo(gg.x), bfhi(gg.x), bflo(gg.y), bfhi(gg.y), bflo(gg.z), bfhi(gg.z), bflo(gg.w), bfhi(gg.w)};
;             bf16_t* mp = mrg + (size_t)row * 1024 + col;
;             if (accum) {
;                 const u32x4 oo = *(const u32x4*)mp;
;                 const float of[8] = {bflo(oo.x), bfhi(oo.x), bflo(oo.y), bfhi(oo.y), bflo(oo.z), bfhi(oo.z), bflo(oo.w), bfhi(oo.w)};
; #pragma unroll
;                 for (int j = 0; j < 8; ++j) v[j] = of[j] + gf[j] * v[j];
;             } else {
; #pragma unroll
;                 for (int j = 0; j < 8; ++j) v[j] = gf[j] * v[j];
;             }
;             *(u32x4*)mp = pack8(v);
;         }
	s_waitcnt lgkmcnt(2)
	v_lshlrev_b32_e32 v184, 16, v144
	v_and_b32_e32 v185, 0xffff0000, v144
	v_lshlrev_b32_e32 v186, 16, v176
	v_and_b32_e32 v187, 0xffff0000, v176
	v_pk_fma_f32 v[244:245], v[244:245], v[184:185], v[186:187]
	v_lshlrev_b32_e32 v184, 16, v145
	v_and_b32_e32 v185, 0xffff0000, v145
	v_lshlrev_b32_e32 v186, 16, v177
	v_and_b32_e32 v187, 0xffff0000, v177
	v_pk_fma_f32 v[246:247], v[246:247], v[184:185], v[186:187]
	v_lshlrev_b32_e32 v184, 16, v146
	v_and_b32_e32 v185, 0xffff0000, v146
	v_lshlrev_b32_e32 v186, 16, v178
	v_and_b32_e32 v187, 0xffff0000, v178
	v_pk_fma_f32 v[220:221], v[220:221], v[184:185], v[186:187]
	v_lshlrev_b32_e32 v184, 16, v147
	v_and_b32_e32 v185, 0xffff0000, v147
	v_lshlrev_b32_e32 v186, 16, v179
	v_and_b32_e32 v187, 0xffff0000, v179
	v_pk_fma_f32 v[222:223], v[222:223], v[184:185], v[186:187]
	v_cvt_pk_bf16_f32 v144, v244, v245
	v_cvt_pk_bf16_f32 v145, v246, v247
	v_cvt_pk_bf16_f32 v146, v220, v221
	v_cvt_pk_bf16_f32 v147, v222, v223
	v_add_u32_e32 v219, 0x4000, v218
	global_store_dwordx4 v219, v[144:147], s[24:25]
	v_add_u32_e32 v219, 12, v212
	v_and_b32_e32 v219, 7, v219
	v_xor_b32_e32 v219, v213, v219
	v_add_u32_e32 v188, 12, v215
	v_lshlrev_b32_e32 v188, 10, v188
	v_lshl_add_u32 v219, v219, 4, v188
	v_xor_b32_e32 v188, 16, v219
	ds_read_b128 v[244:247], v219
	ds_read_b128 v[220:223], v188
	s_waitcnt vmcnt(9)
	s_waitcnt lgkmcnt(2)
	v_lshlrev_b32_e32 v184, 16, v148
	v_and_b32_e32 v185, 0xffff0000, v148
	v_lshlrev_b32_e32 v186, 16, v180
	v_and_b32_e32 v187, 0xffff0000, v180
	v_pk_fma_f32 v[234:235], v[234:235], v[184:185], v[186:187]
	v_lshlrev_b32_e32 v184, 16, v149
	v_and_b32_e32 v185, 0xffff0000, v149
	v_lshlrev_b32_e32 v186, 16, v181
	v_and_b32_e32 v187, 0xffff0000, v181
	v_pk_fma_f32 v[236:237], v[236:237], v[184:185], v[186:187]
	v_lshlrev_b32_e32 v184, 16, v150
	v_and_b32_e32 v185, 0xffff0000, v150
	v_lshlrev_b32_e32 v186, 16, v182
	v_and_b32_e32 v187, 0xffff0000, v182
	v_pk_fma_f32 v[228:229], v[228:229], v[184:185], v[186:187]
	v_lshlrev_b32_e32 v184, 16, v151
	v_and_b32_e32 v185, 0xffff0000, v151
	v_lshlrev_b32_e32 v186, 16, v183
	v_and_b32_e32 v187, 0xffff0000, v183
	v_pk_fma_f32 v[230:231], v[230:231], v[184:185], v[186:187]
	v_cvt_pk_bf16_f32 v148, v234, v235
	v_cvt_pk_bf16_f32 v149, v236, v237
	v_cvt_pk_bf16_f32 v150, v228, v229
	v_cvt_pk_bf16_f32 v151, v230, v231
	v_add_u32_e32 v219, 0x5000, v218
	global_store_dwordx4 v219, v[148:151], s[24:25]
	v_add_u32_e32 v219, 14, v212
	v_and_b32_e32 v219, 7, v219
	v_xor_b32_e32 v219, v213, v219
	v_add_u32_e32 v188, 14, v215
	v_lshlrev_b32_e32 v188, 10, v188
	v_lshl_add_u32 v219, v219, 4, v188
	v_xor_b32_e32 v188, 16, v219
	ds_read_b128 v[234:237], v219
	ds_read_b128 v[228:231], v188
	s_waitcnt vmcnt(8)
	s_waitcnt lgkmcnt(2)
	v_lshlrev_b32_e32 v184, 16, v152
	v_and_b32_e32 v185, 0xffff0000, v152
	v_lshlrev_b32_e32 v186, 16, v224
	v_and_b32_e32 v187, 0xffff0000, v224
	v_pk_fma_f32 v[244:245], v[244:245], v[184:185], v[186:187]
	v_lshlrev_b32_e32 v184, 16, v153
	v_and_b32_e32 v185, 0xffff0000, v153
	v_lshlrev_b32_e32 v186, 16, v225
	v_and_b32_e32 v187, 0xffff0000, v225
	v_pk_fma_f32 v[246:247], v[246:247], v[184:185], v[186:187]
	v_lshlrev_b32_e32 v184, 16, v154
	v_and_b32_e32 v185, 0xffff0000, v154
	v_lshlrev_b32_e32 v186, 16, v226
	v_and_b32_e32 v187, 0xffff0000, v226
	v_pk_fma_f32 v[220:221], v[220:221], v[184:185], v[186:187]
	v_lshlrev_b32_e32 v184, 16, v155
	v_and_b32_e32 v185, 0xffff0000, v155
	v_lshlrev_b32_e32 v186, 16, v227
	v_and_b32_e32 v187, 0xffff0000, v227
	v_pk_fma_f32 v[222:223], v[222:223], v[184:185], v[186:187]
	v_cvt_pk_bf16_f32 v152, v244, v245
	v_cvt_pk_bf16_f32 v153, v246, v247
	v_cvt_pk_bf16_f32 v154, v220, v221
	v_cvt_pk_bf16_f32 v155, v222, v223
	v_add_u32_e32 v219, 0x6000, v218
	global_store_dwordx4 v219, v[152:155], s[24:25]
	s_waitcnt vmcnt(7)
	s_waitcnt lgkmcnt(0)
	v_lshlrev_b32_e32 v184, 16, v156
	v_and_b32_e32 v185, 0xffff0000, v156
	v_lshlrev_b32_e32 v186, 16, v240
	v_and_b32_e32 v187, 0xffff0000, v240
	v_pk_fma_f32 v[234:235], v[234:235], v[184:185], v[186:187]
	v_lshlrev_b32_e32 v184, 16, v157
	v_and_b32_e32 v185, 0xffff0000, v157
	v_lshlrev_b32_e32 v186, 16, v241
	v_and_b32_e32 v187, 0xffff0000, v241
	v_pk_fma_f32 v[236:237], v[236:237], v[184:185], v[186:187]
	v_lshlrev_b32_e32 v184, 16, v158
	v_and_b32_e32 v185, 0xffff0000, v158
	v_lshlrev_b32_e32 v186, 16, v242
	v_and_b32_e32 v187, 0xffff0000, v242
	v_pk_fma_f32 v[228:229], v[228:229], v[184:185], v[186:187]
	v_lshlrev_b32_e32 v184, 16, v159
	v_and_b32_e32 v185, 0xffff0000, v159
	v_lshlrev_b32_e32 v186, 16, v243
	v_and_b32_e32 v187, 0xffff0000, v243
	v_pk_fma_f32 v[230:231], v[230:231], v[184:185], v[186:187]
	v_cvt_pk_bf16_f32 v156, v234, v235
	v_cvt_pk_bf16_f32 v157, v236, v237
	v_cvt_pk_bf16_f32 v158, v228, v229
	v_cvt_pk_bf16_f32 v159, v230, v231
	v_add_u32_e32 v219, 0x7000, v218
	global_store_dwordx4 v219, v[156:159], s[24:25]
	s_mov_b64 s[6:7], -1
	s_and_b64 vcc, exec, s[14:15]
	s_cbranch_vccnz .LBB0_1233
	s_andn2_b64 vcc, exec, s[20:21]
	s_cbranch_vccnz .LBB0_1232
	s_barrier
	s_branch .LBB0_1232
